# v28 + merge-gate epilogue: x*2^-6 then *(-log2 e) fused into one multiply (bit-identical); instruction count kept near lane-permutes and memory ops
# speedup vs baseline: 1.0091x; 1.0049x over previous
.LBB0_123:
	s_andn2_b64 vcc, exec, s[6:7]
	s_cbranch_vccnz .LBB0_125
	v_mul_f32_e32 v134, 0xbcb8aa3b, v128
	v_mul_f32_e32 v139, 0xbcb8aa3b, v129
	v_exp_f32_e32 v134, v134
	v_mul_f32_e32 v156, 0xbcb8aa3b, v130
	v_mul_f32_e32 v135, 0xbcb8aa3b, v124
	v_exp_f32_e32 v139, v139
	v_mul_f32_e32 v158, 0xbcb8aa3b, v131
	v_mul_f32_e32 v155, 0xbcb8aa3b, v125
	v_exp_f32_e32 v156, v156
	v_exp_f32_e32 v135, v135
	v_mul_f32_e32 v157, 0xbcb8aa3b, v126
	v_exp_f32_e32 v158, v158
	v_add_f32_e32 v134, 1.0, v134
	v_exp_f32_e32 v155, v155
	v_mul_f32_e32 v159, 0xbcb8aa3b, v127
	v_rcp_f32_e32 v137, v134
	v_add_f32_e32 v139, 1.0, v139
	v_exp_f32_e32 v157, v157
	v_rcp_f32_e32 v139, v139
	v_add_f32_e32 v156, 1.0, v156
	v_exp_f32_e32 v159, v159
	v_add_f32_e32 v134, 1.0, v135
	v_rcp_f32_e32 v156, v156
	v_add_f32_e32 v158, 1.0, v158
	v_rcp_f32_e32 v138, v134
	s_mov_b32 s9, 0x437f0000
	v_add_f32_e32 v155, 1.0, v155
	v_rcp_f32_e32 v158, v158
	v_fma_f32 v137, v137, s9, 0.5
	v_rcp_f32_e32 v155, v155
	v_add_f32_e32 v157, 1.0, v157
	v_or_b32_e32 v132, 0xffffb800, v163
	v_max_f32_e32 v137, 1.0, v137
	v_fma_f32 v139, v139, s9, 0.5
	v_rcp_f32_e32 v157, v157
	v_add_f32_e32 v159, 1.0, v159
	v_lshl_add_u32 v132, s76, 8, v132
	v_max_f32_e32 v139, 1.0, v139
	v_fma_f32 v156, v156, s9, 0.5
	v_rcp_f32_e32 v159, v159
	v_cvt_pk_u8_f32 v137, v137, 0, 0
	v_fma_f32 v138, v138, s9, 0.5
	v_bfe_u32 v133, v132, 3, 1
	v_max_f32_e32 v156, 1.0, v156
	v_fma_f32 v158, v158, s9, 0.5
	v_cvt_pk_u8_f32 v137, v139, 1, v137
	v_lshl_or_b32 v136, v133, 4, v154
	v_lshlrev_b32_e32 v133, 3, v133
	v_max_f32_e32 v138, 1.0, v138
	v_fma_f32 v155, v155, s9, 0.5
	v_max_f32_e32 v158, 1.0, v158
	v_cvt_pk_u8_f32 v137, v156, 2, v137
	v_sub_u32_e32 v132, v132, v133
	v_max_f32_e32 v155, 1.0, v155
	v_fma_f32 v157, v157, s9, 0.5
	v_cvt_pk_u8_f32 v156, v158, 3, v137
	v_cvt_pk_u8_f32 v137, v138, 0, 0
	v_ashrrev_i32_e32 v133, 31, v132
	v_max_f32_e32 v157, 1.0, v157
	v_fma_f32 v159, v159, s9, 0.5
	v_cvt_pk_u8_f32 v137, v155, 1, v137
	v_lshl_add_u64 v[132:133], s[58:59], 0, v[132:133]
	s_movk_i32 s8, 0x3000
	v_max_f32_e32 v159, 1.0, v159
	v_cvt_pk_u8_f32 v137, v157, 2, v137
	v_mad_i64_i32 v[134:135], s[6:7], v136, s8, v[132:133]
	v_cvt_pk_u8_f32 v157, v159, 3, v137
	v_mul_f32_e32 v137, 0xbcb8aa3b, v112
	v_mul_f32_e32 v139, 0xbcb8aa3b, v113
	v_exp_f32_e32 v137, v137
	v_mul_f32_e32 v158, 0xbcb8aa3b, v114
	v_mul_f32_e32 v138, 0xbcb8aa3b, v108
	v_exp_f32_e32 v139, v139
	v_mul_f32_e32 v160, 0xbcb8aa3b, v115
	v_mul_f32_e32 v155, 0xbcb8aa3b, v109
	v_exp_f32_e32 v158, v158
	v_exp_f32_e32 v138, v138
	v_mul_f32_e32 v159, 0xbcb8aa3b, v110
	v_exp_f32_e32 v160, v160
	v_add_f32_e32 v137, 1.0, v137
	v_exp_f32_e32 v155, v155
	v_mul_f32_e32 v161, 0xbcb8aa3b, v111
	v_rcp_f32_e32 v137, v137
	v_add_f32_e32 v139, 1.0, v139
	v_exp_f32_e32 v159, v159
	v_rcp_f32_e32 v139, v139
	v_add_f32_e32 v158, 1.0, v158
	v_exp_f32_e32 v161, v161
	v_add_f32_e32 v138, 1.0, v138
	v_rcp_f32_e32 v158, v158
	v_add_f32_e32 v160, 1.0, v160
	v_rcp_f32_e32 v138, v138
	v_add_f32_e32 v155, 1.0, v155
	v_rcp_f32_e32 v160, v160
	v_fma_f32 v137, v137, s9, 0.5
	v_rcp_f32_e32 v155, v155
	v_add_f32_e32 v159, 1.0, v159
	v_max_f32_e32 v137, 1.0, v137
	v_fma_f32 v139, v139, s9, 0.5
	v_rcp_f32_e32 v159, v159
	v_add_f32_e32 v161, 1.0, v161
	v_max_f32_e32 v139, 1.0, v139
	v_fma_f32 v158, v158, s9, 0.5
	v_rcp_f32_e32 v161, v161
	v_cvt_pk_u8_f32 v137, v137, 0, 0
	v_fma_f32 v138, v138, s9, 0.5
	v_max_f32_e32 v158, 1.0, v158
	v_fma_f32 v160, v160, s9, 0.5
	v_cvt_pk_u8_f32 v137, v139, 1, v137
	v_max_f32_e32 v138, 1.0, v138
	v_fma_f32 v155, v155, s9, 0.5
	v_max_f32_e32 v160, 1.0, v160
	v_cvt_pk_u8_f32 v137, v158, 2, v137
	v_max_f32_e32 v155, 1.0, v155
	v_fma_f32 v159, v159, s9, 0.5
	v_cvt_pk_u8_f32 v158, v160, 3, v137
	v_cvt_pk_u8_f32 v137, v138, 0, 0
	v_max_f32_e32 v159, 1.0, v159
	v_fma_f32 v161, v161, s9, 0.5
	v_cvt_pk_u8_f32 v137, v155, 1, v137
	v_max_f32_e32 v161, 1.0, v161
	v_cvt_pk_u8_f32 v137, v159, 2, v137
	v_cvt_pk_u8_f32 v159, v161, 3, v137
	v_mul_f32_e32 v137, 0xbcb8aa3b, v120
	v_permlane16_swap_b32_e32 v156, v158
	s_nop 0
	v_permlane16_swap_b32_e32 v157, v159
	v_mul_f32_e32 v139, 0xbcb8aa3b, v121
	v_exp_f32_e32 v137, v137
	global_store_dwordx4 v[134:135], v[156:159], off
	s_nop 0
	v_mul_f32_e32 v138, 0xbcb8aa3b, v116
	v_mul_f32_e32 v156, 0xbcb8aa3b, v122
	v_exp_f32_e32 v139, v139
	v_mul_f32_e32 v158, 0xbcb8aa3b, v123
	v_mul_f32_e32 v155, 0xbcb8aa3b, v117
	v_exp_f32_e32 v156, v156
	v_exp_f32_e32 v138, v138
	v_mul_f32_e32 v157, 0xbcb8aa3b, v118
	v_exp_f32_e32 v158, v158
	v_add_f32_e32 v137, 1.0, v137
	v_exp_f32_e32 v155, v155
	v_mul_f32_e32 v159, 0xbcb8aa3b, v119
	v_rcp_f32_e32 v137, v137
	v_add_f32_e32 v139, 1.0, v139
	v_exp_f32_e32 v157, v157
	v_rcp_f32_e32 v139, v139
	v_add_f32_e32 v156, 1.0, v156
	v_exp_f32_e32 v159, v159
	v_add_f32_e32 v138, 1.0, v138
	v_rcp_f32_e32 v156, v156
	v_add_f32_e32 v158, 1.0, v158
	v_rcp_f32_e32 v138, v138
	v_add_f32_e32 v155, 1.0, v155
	v_rcp_f32_e32 v158, v158
	v_fma_f32 v137, v137, s9, 0.5
	v_rcp_f32_e32 v155, v155
	v_add_f32_e32 v157, 1.0, v157
	v_max_f32_e32 v137, 1.0, v137
	v_fma_f32 v139, v139, s9, 0.5
	v_rcp_f32_e32 v157, v157
	v_add_f32_e32 v159, 1.0, v159
	v_max_f32_e32 v139, 1.0, v139
	v_fma_f32 v156, v156, s9, 0.5
	v_rcp_f32_e32 v159, v159
	v_cvt_pk_u8_f32 v137, v137, 0, 0
	v_fma_f32 v138, v138, s9, 0.5
	v_max_f32_e32 v156, 1.0, v156
	v_fma_f32 v158, v158, s9, 0.5
	v_cvt_pk_u8_f32 v137, v139, 1, v137
	v_max_f32_e32 v138, 1.0, v138
	v_fma_f32 v155, v155, s9, 0.5
	v_max_f32_e32 v158, 1.0, v158
	v_cvt_pk_u8_f32 v137, v156, 2, v137
	v_max_f32_e32 v155, 1.0, v155
	v_fma_f32 v157, v157, s9, 0.5
	v_cvt_pk_u8_f32 v156, v158, 3, v137
	v_cvt_pk_u8_f32 v137, v138, 0, 0
	v_max_f32_e32 v157, 1.0, v157
	v_fma_f32 v159, v159, s9, 0.5
	v_cvt_pk_u8_f32 v137, v155, 1, v137
	v_max_f32_e32 v159, 1.0, v159
	v_cvt_pk_u8_f32 v137, v157, 2, v137
	v_cvt_pk_u8_f32 v157, v159, 3, v137
	v_mul_f32_e32 v137, 0xbcb8aa3b, v104
	v_mul_f32_e32 v139, 0xbcb8aa3b, v105
	v_exp_f32_e32 v137, v137
	v_mul_f32_e32 v158, 0xbcb8aa3b, v106
	v_mul_f32_e32 v138, 0xbcb8aa3b, v100
	v_exp_f32_e32 v139, v139
	v_mul_f32_e32 v160, 0xbcb8aa3b, v107
	v_mul_f32_e32 v155, 0xbcb8aa3b, v101
	v_exp_f32_e32 v158, v158
	v_exp_f32_e32 v138, v138
	v_mul_f32_e32 v159, 0xbcb8aa3b, v102
	v_exp_f32_e32 v160, v160
	v_add_f32_e32 v137, 1.0, v137
	v_exp_f32_e32 v155, v155
	v_mul_f32_e32 v161, 0xbcb8aa3b, v103
	v_rcp_f32_e32 v137, v137
	v_add_f32_e32 v139, 1.0, v139
	v_exp_f32_e32 v159, v159
	v_rcp_f32_e32 v139, v139
	v_add_f32_e32 v158, 1.0, v158
	v_exp_f32_e32 v161, v161
	v_add_f32_e32 v138, 1.0, v138
	v_rcp_f32_e32 v158, v158
	v_add_f32_e32 v160, 1.0, v160
	v_rcp_f32_e32 v138, v138
	v_add_f32_e32 v155, 1.0, v155
	v_rcp_f32_e32 v160, v160
	v_fma_f32 v137, v137, s9, 0.5
	v_rcp_f32_e32 v155, v155
	v_add_f32_e32 v159, 1.0, v159
	v_max_f32_e32 v137, 1.0, v137
	v_fma_f32 v139, v139, s9, 0.5
	v_rcp_f32_e32 v159, v159
	v_add_f32_e32 v161, 1.0, v161
	v_max_f32_e32 v139, 1.0, v139
	v_fma_f32 v158, v158, s9, 0.5
	v_rcp_f32_e32 v161, v161
	v_cvt_pk_u8_f32 v137, v137, 0, 0
	v_fma_f32 v138, v138, s9, 0.5
	v_max_f32_e32 v158, 1.0, v158
	v_fma_f32 v160, v160, s9, 0.5
	v_cvt_pk_u8_f32 v137, v139, 1, v137
	v_max_f32_e32 v138, 1.0, v138
	v_fma_f32 v155, v155, s9, 0.5
	v_max_f32_e32 v160, 1.0, v160
	v_cvt_pk_u8_f32 v137, v158, 2, v137
	v_max_f32_e32 v155, 1.0, v155
	v_fma_f32 v159, v159, s9, 0.5
	v_cvt_pk_u8_f32 v158, v160, 3, v137
	v_cvt_pk_u8_f32 v137, v138, 0, 0
	v_max_f32_e32 v159, 1.0, v159
	v_fma_f32 v161, v161, s9, 0.5
	v_cvt_pk_u8_f32 v137, v155, 1, v137
	v_max_f32_e32 v161, 1.0, v161
	v_cvt_pk_u8_f32 v137, v159, 2, v137
	v_cvt_pk_u8_f32 v159, v161, 3, v137
	v_permlane16_swap_b32_e32 v156, v158
	s_nop 0
	v_permlane16_swap_b32_e32 v157, v159
	global_store_dwordx4 v[134:135], v[156:159], off offset:128
	v_mul_f32_e32 v134, 0xbcb8aa3b, v96
	s_nop 0
	v_mul_f32_e32 v135, 0xbcb8aa3b, v92
	v_exp_f32_e32 v134, v134
	v_exp_f32_e32 v135, v135
	v_or_b32_e32 v137, 32, v136
	v_add_f32_e32 v134, 1.0, v134
	v_rcp_f32_e32 v138, v134
	v_add_f32_e32 v134, 1.0, v135
	v_rcp_f32_e32 v139, v134
	v_mad_i64_i32 v[134:135], s[6:7], v137, s8, v[132:133]
	v_fma_f32 v137, v138, s9, 0.5
	v_fma_f32 v138, v139, s9, 0.5
	v_mul_f32_e32 v139, 0xbcb8aa3b, v97
	v_mul_f32_e32 v156, 0xbcb8aa3b, v98
	v_exp_f32_e32 v139, v139
	v_mul_f32_e32 v158, 0xbcb8aa3b, v99
	v_mul_f32_e32 v155, 0xbcb8aa3b, v93
	v_exp_f32_e32 v156, v156
	v_mul_f32_e32 v157, 0xbcb8aa3b, v94
	v_exp_f32_e32 v158, v158
	v_exp_f32_e32 v155, v155
	v_mul_f32_e32 v159, 0xbcb8aa3b, v95
	v_add_f32_e32 v139, 1.0, v139
	v_exp_f32_e32 v157, v157
	v_rcp_f32_e32 v139, v139
	v_add_f32_e32 v156, 1.0, v156
	v_exp_f32_e32 v159, v159
	v_rcp_f32_e32 v156, v156
	v_add_f32_e32 v158, 1.0, v158
	v_add_f32_e32 v155, 1.0, v155
	v_rcp_f32_e32 v158, v158
	v_rcp_f32_e32 v155, v155
	v_add_f32_e32 v157, 1.0, v157
	v_max_f32_e32 v137, 1.0, v137
	v_fma_f32 v139, v139, s9, 0.5
	v_rcp_f32_e32 v157, v157
	v_add_f32_e32 v159, 1.0, v159
	v_max_f32_e32 v139, 1.0, v139
	v_fma_f32 v156, v156, s9, 0.5
	v_rcp_f32_e32 v159, v159
	v_cvt_pk_u8_f32 v137, v137, 0, 0
	v_max_f32_e32 v156, 1.0, v156
	v_fma_f32 v158, v158, s9, 0.5
	v_cvt_pk_u8_f32 v137, v139, 1, v137
	v_max_f32_e32 v138, 1.0, v138
	v_fma_f32 v155, v155, s9, 0.5
	v_max_f32_e32 v158, 1.0, v158
	v_cvt_pk_u8_f32 v137, v156, 2, v137
	v_max_f32_e32 v155, 1.0, v155
	v_fma_f32 v157, v157, s9, 0.5
	v_cvt_pk_u8_f32 v156, v158, 3, v137
	v_cvt_pk_u8_f32 v137, v138, 0, 0
	v_max_f32_e32 v157, 1.0, v157
	v_fma_f32 v159, v159, s9, 0.5
	v_cvt_pk_u8_f32 v137, v155, 1, v137
	v_max_f32_e32 v159, 1.0, v159
	v_cvt_pk_u8_f32 v137, v157, 2, v137
	v_cvt_pk_u8_f32 v157, v159, 3, v137
	v_mul_f32_e32 v137, 0xbcb8aa3b, v80
	v_mul_f32_e32 v139, 0xbcb8aa3b, v81
	v_exp_f32_e32 v137, v137
	v_mul_f32_e32 v158, 0xbcb8aa3b, v82
	v_mul_f32_e32 v138, 0xbcb8aa3b, v76
	v_exp_f32_e32 v139, v139
	v_mul_f32_e32 v160, 0xbcb8aa3b, v83
	v_mul_f32_e32 v155, 0xbcb8aa3b, v77
	v_exp_f32_e32 v158, v158
	v_exp_f32_e32 v138, v138
	v_mul_f32_e32 v159, 0xbcb8aa3b, v78
	v_exp_f32_e32 v160, v160
	v_add_f32_e32 v137, 1.0, v137
	v_exp_f32_e32 v155, v155
	v_mul_f32_e32 v161, 0xbcb8aa3b, v79
	v_rcp_f32_e32 v137, v137
	v_add_f32_e32 v139, 1.0, v139
	v_exp_f32_e32 v159, v159
	v_rcp_f32_e32 v139, v139
	v_add_f32_e32 v158, 1.0, v158
	v_exp_f32_e32 v161, v161
	v_add_f32_e32 v138, 1.0, v138
	v_rcp_f32_e32 v158, v158
	v_add_f32_e32 v160, 1.0, v160
	v_rcp_f32_e32 v138, v138
	v_add_f32_e32 v155, 1.0, v155
	v_rcp_f32_e32 v160, v160
	v_fma_f32 v137, v137, s9, 0.5
	v_rcp_f32_e32 v155, v155
	v_add_f32_e32 v159, 1.0, v159
	v_max_f32_e32 v137, 1.0, v137
	v_fma_f32 v139, v139, s9, 0.5
	v_rcp_f32_e32 v159, v159
	v_add_f32_e32 v161, 1.0, v161
	v_max_f32_e32 v139, 1.0, v139
	v_fma_f32 v158, v158, s9, 0.5
	v_rcp_f32_e32 v161, v161
	v_cvt_pk_u8_f32 v137, v137, 0, 0
	v_fma_f32 v138, v138, s9, 0.5
	v_max_f32_e32 v158, 1.0, v158
	v_fma_f32 v160, v160, s9, 0.5
	v_cvt_pk_u8_f32 v137, v139, 1, v137
	v_max_f32_e32 v138, 1.0, v138
	v_fma_f32 v155, v155, s9, 0.5
	v_max_f32_e32 v160, 1.0, v160
	v_cvt_pk_u8_f32 v137, v158, 2, v137
	v_max_f32_e32 v155, 1.0, v155
	v_fma_f32 v159, v159, s9, 0.5
	v_cvt_pk_u8_f32 v158, v160, 3, v137
	v_cvt_pk_u8_f32 v137, v138, 0, 0
	v_max_f32_e32 v159, 1.0, v159
	v_fma_f32 v161, v161, s9, 0.5
	v_cvt_pk_u8_f32 v137, v155, 1, v137
	v_max_f32_e32 v161, 1.0, v161
	v_cvt_pk_u8_f32 v137, v159, 2, v137
	v_cvt_pk_u8_f32 v159, v161, 3, v137
	v_mul_f32_e32 v137, 0xbcb8aa3b, v88
	v_permlane16_swap_b32_e32 v156, v158
	s_nop 0
	v_permlane16_swap_b32_e32 v157, v159
	v_mul_f32_e32 v139, 0xbcb8aa3b, v89
	v_exp_f32_e32 v137, v137
	global_store_dwordx4 v[134:135], v[156:159], off
	s_nop 0
	v_mul_f32_e32 v138, 0xbcb8aa3b, v84
	v_mul_f32_e32 v156, 0xbcb8aa3b, v90
	v_exp_f32_e32 v139, v139
	v_mul_f32_e32 v158, 0xbcb8aa3b, v91
	v_mul_f32_e32 v155, 0xbcb8aa3b, v85
	v_exp_f32_e32 v156, v156
	v_exp_f32_e32 v138, v138
	v_mul_f32_e32 v157, 0xbcb8aa3b, v86
	v_exp_f32_e32 v158, v158
	v_add_f32_e32 v137, 1.0, v137
	v_exp_f32_e32 v155, v155
	v_mul_f32_e32 v159, 0xbcb8aa3b, v87
	v_rcp_f32_e32 v137, v137
	v_add_f32_e32 v139, 1.0, v139
	v_exp_f32_e32 v157, v157
	v_rcp_f32_e32 v139, v139
	v_add_f32_e32 v156, 1.0, v156
	v_exp_f32_e32 v159, v159
	v_add_f32_e32 v138, 1.0, v138
	v_rcp_f32_e32 v156, v156
	v_add_f32_e32 v158, 1.0, v158
	v_rcp_f32_e32 v138, v138
	v_add_f32_e32 v155, 1.0, v155
	v_rcp_f32_e32 v158, v158
	v_fma_f32 v137, v137, s9, 0.5
	v_rcp_f32_e32 v155, v155
	v_add_f32_e32 v157, 1.0, v157
	v_max_f32_e32 v137, 1.0, v137
	v_fma_f32 v139, v139, s9, 0.5
	v_rcp_f32_e32 v157, v157
	v_add_f32_e32 v159, 1.0, v159
	v_max_f32_e32 v139, 1.0, v139
	v_fma_f32 v156, v156, s9, 0.5
	v_rcp_f32_e32 v159, v159
	v_cvt_pk_u8_f32 v137, v137, 0, 0
	v_fma_f32 v138, v138, s9, 0.5
	v_max_f32_e32 v156, 1.0, v156
	v_fma_f32 v158, v158, s9, 0.5
	v_cvt_pk_u8_f32 v137, v139, 1, v137
	v_max_f32_e32 v138, 1.0, v138
	v_fma_f32 v155, v155, s9, 0.5
	v_max_f32_e32 v158, 1.0, v158
	v_cvt_pk_u8_f32 v137, v156, 2, v137
	v_max_f32_e32 v155, 1.0, v155
	v_fma_f32 v157, v157, s9, 0.5
	v_cvt_pk_u8_f32 v156, v158, 3, v137
	v_cvt_pk_u8_f32 v137, v138, 0, 0
	v_max_f32_e32 v157, 1.0, v157
	v_fma_f32 v159, v159, s9, 0.5
	v_cvt_pk_u8_f32 v137, v155, 1, v137
	v_max_f32_e32 v159, 1.0, v159
	v_cvt_pk_u8_f32 v137, v157, 2, v137
	v_cvt_pk_u8_f32 v157, v159, 3, v137
	v_mul_f32_e32 v137, 0xbcb8aa3b, v72
	v_mul_f32_e32 v139, 0xbcb8aa3b, v73
	v_exp_f32_e32 v137, v137
	v_mul_f32_e32 v158, 0xbcb8aa3b, v74
	v_mul_f32_e32 v138, 0xbcb8aa3b, v68
	v_exp_f32_e32 v139, v139
	v_mul_f32_e32 v160, 0xbcb8aa3b, v75
	v_mul_f32_e32 v155, 0xbcb8aa3b, v69
	v_exp_f32_e32 v158, v158
	v_exp_f32_e32 v138, v138
	v_mul_f32_e32 v159, 0xbcb8aa3b, v70
	v_exp_f32_e32 v160, v160
	v_add_f32_e32 v137, 1.0, v137
	v_exp_f32_e32 v155, v155
	v_mul_f32_e32 v161, 0xbcb8aa3b, v71
	v_rcp_f32_e32 v137, v137
	v_add_f32_e32 v139, 1.0, v139
	v_exp_f32_e32 v159, v159
	v_rcp_f32_e32 v139, v139
	v_add_f32_e32 v158, 1.0, v158
	v_exp_f32_e32 v161, v161
	v_add_f32_e32 v138, 1.0, v138
	v_rcp_f32_e32 v158, v158
	v_add_f32_e32 v160, 1.0, v160
	v_rcp_f32_e32 v138, v138
	v_add_f32_e32 v155, 1.0, v155
	v_rcp_f32_e32 v160, v160
	v_fma_f32 v137, v137, s9, 0.5
	v_rcp_f32_e32 v155, v155
	v_add_f32_e32 v159, 1.0, v159
	v_max_f32_e32 v137, 1.0, v137
	v_fma_f32 v139, v139, s9, 0.5
	v_rcp_f32_e32 v159, v159
	v_add_f32_e32 v161, 1.0, v161
	v_max_f32_e32 v139, 1.0, v139
	v_fma_f32 v158, v158, s9, 0.5
	v_rcp_f32_e32 v161, v161
	v_cvt_pk_u8_f32 v137, v137, 0, 0
	v_fma_f32 v138, v138, s9, 0.5
	v_max_f32_e32 v158, 1.0, v158
	v_fma_f32 v160, v160, s9, 0.5
	v_cvt_pk_u8_f32 v137, v139, 1, v137
	v_max_f32_e32 v138, 1.0, v138
	v_fma_f32 v155, v155, s9, 0.5
	v_max_f32_e32 v160, 1.0, v160
	v_cvt_pk_u8_f32 v137, v158, 2, v137
	v_max_f32_e32 v155, 1.0, v155
	v_fma_f32 v159, v159, s9, 0.5
	v_cvt_pk_u8_f32 v158, v160, 3, v137
	v_cvt_pk_u8_f32 v137, v138, 0, 0
	v_max_f32_e32 v159, 1.0, v159
	v_fma_f32 v161, v161, s9, 0.5
	v_cvt_pk_u8_f32 v137, v155, 1, v137
	v_max_f32_e32 v161, 1.0, v161
	v_cvt_pk_u8_f32 v137, v159, 2, v137
	v_cvt_pk_u8_f32 v159, v161, 3, v137
	v_permlane16_swap_b32_e32 v156, v158
	s_nop 0
	v_permlane16_swap_b32_e32 v157, v159
	global_store_dwordx4 v[134:135], v[156:159], off offset:128
	v_mul_f32_e32 v134, 0xbcb8aa3b, v64
	s_nop 0
	v_mul_f32_e32 v135, 0xbcb8aa3b, v60
	v_exp_f32_e32 v134, v134
	v_exp_f32_e32 v135, v135
	v_add_u32_e32 v137, 0x80, v136
	v_add_f32_e32 v134, 1.0, v134
	v_rcp_f32_e32 v138, v134
	v_add_f32_e32 v134, 1.0, v135
	v_rcp_f32_e32 v139, v134
	v_mad_i64_i32 v[134:135], s[6:7], v137, s8, v[132:133]
	v_fma_f32 v137, v138, s9, 0.5
	v_fma_f32 v138, v139, s9, 0.5
	v_mul_f32_e32 v139, 0xbcb8aa3b, v65
	v_mul_f32_e32 v156, 0xbcb8aa3b, v66
	v_exp_f32_e32 v139, v139
	v_mul_f32_e32 v158, 0xbcb8aa3b, v67
	v_mul_f32_e32 v155, 0xbcb8aa3b, v61
	v_exp_f32_e32 v156, v156
	v_mul_f32_e32 v157, 0xbcb8aa3b, v62
	v_exp_f32_e32 v158, v158
	v_exp_f32_e32 v155, v155
	v_mul_f32_e32 v159, 0xbcb8aa3b, v63
	v_add_f32_e32 v139, 1.0, v139
	v_exp_f32_e32 v157, v157
	v_rcp_f32_e32 v139, v139
	v_add_f32_e32 v156, 1.0, v156
	v_exp_f32_e32 v159, v159
	v_rcp_f32_e32 v156, v156
	v_add_f32_e32 v158, 1.0, v158
	v_add_f32_e32 v155, 1.0, v155
	v_rcp_f32_e32 v158, v158
	v_rcp_f32_e32 v155, v155
	v_add_f32_e32 v157, 1.0, v157
	v_max_f32_e32 v137, 1.0, v137
	v_fma_f32 v139, v139, s9, 0.5
	v_rcp_f32_e32 v157, v157
	v_add_f32_e32 v159, 1.0, v159
	v_max_f32_e32 v139, 1.0, v139
	v_fma_f32 v156, v156, s9, 0.5
	v_rcp_f32_e32 v159, v159
	v_cvt_pk_u8_f32 v137, v137, 0, 0
	v_max_f32_e32 v156, 1.0, v156
	v_fma_f32 v158, v158, s9, 0.5
	v_cvt_pk_u8_f32 v137, v139, 1, v137
	v_max_f32_e32 v138, 1.0, v138
	v_fma_f32 v155, v155, s9, 0.5
	v_max_f32_e32 v158, 1.0, v158
	v_cvt_pk_u8_f32 v137, v156, 2, v137
	v_max_f32_e32 v155, 1.0, v155
	v_fma_f32 v157, v157, s9, 0.5
	v_cvt_pk_u8_f32 v156, v158, 3, v137
	v_cvt_pk_u8_f32 v137, v138, 0, 0
	v_max_f32_e32 v157, 1.0, v157
	v_fma_f32 v159, v159, s9, 0.5
	v_cvt_pk_u8_f32 v137, v155, 1, v137
	v_max_f32_e32 v159, 1.0, v159
	v_cvt_pk_u8_f32 v137, v157, 2, v137
	v_cvt_pk_u8_f32 v157, v159, 3, v137
	v_mul_f32_e32 v137, 0xbcb8aa3b, v48
	v_mul_f32_e32 v139, 0xbcb8aa3b, v49
	v_exp_f32_e32 v137, v137
	v_mul_f32_e32 v158, 0xbcb8aa3b, v50
	v_mul_f32_e32 v138, 0xbcb8aa3b, v44
	v_exp_f32_e32 v139, v139
	v_mul_f32_e32 v160, 0xbcb8aa3b, v51
	v_mul_f32_e32 v155, 0xbcb8aa3b, v45
	v_exp_f32_e32 v158, v158
	v_exp_f32_e32 v138, v138
	v_mul_f32_e32 v159, 0xbcb8aa3b, v46
	v_exp_f32_e32 v160, v160
	v_add_f32_e32 v137, 1.0, v137
	v_exp_f32_e32 v155, v155
	v_mul_f32_e32 v161, 0xbcb8aa3b, v47
	v_rcp_f32_e32 v137, v137
	v_add_f32_e32 v139, 1.0, v139
	v_exp_f32_e32 v159, v159
	v_rcp_f32_e32 v139, v139
	v_add_f32_e32 v158, 1.0, v158
	v_exp_f32_e32 v161, v161
	v_add_f32_e32 v138, 1.0, v138
	v_rcp_f32_e32 v158, v158
	v_add_f32_e32 v160, 1.0, v160
	v_rcp_f32_e32 v138, v138
	v_add_f32_e32 v155, 1.0, v155
	v_rcp_f32_e32 v160, v160
	v_fma_f32 v137, v137, s9, 0.5
	v_rcp_f32_e32 v155, v155
	v_add_f32_e32 v159, 1.0, v159
	v_max_f32_e32 v137, 1.0, v137
	v_fma_f32 v139, v139, s9, 0.5
	v_rcp_f32_e32 v159, v159
	v_add_f32_e32 v161, 1.0, v161
	v_max_f32_e32 v139, 1.0, v139
	v_fma_f32 v158, v158, s9, 0.5
	v_rcp_f32_e32 v161, v161
	v_cvt_pk_u8_f32 v137, v137, 0, 0
	v_fma_f32 v138, v138, s9, 0.5
	v_max_f32_e32 v158, 1.0, v158
	v_fma_f32 v160, v160, s9, 0.5
	v_cvt_pk_u8_f32 v137, v139, 1, v137
	v_max_f32_e32 v138, 1.0, v138
	v_fma_f32 v155, v155, s9, 0.5
	v_max_f32_e32 v160, 1.0, v160
	v_cvt_pk_u8_f32 v137, v158, 2, v137
	v_max_f32_e32 v155, 1.0, v155
	v_fma_f32 v159, v159, s9, 0.5
	v_cvt_pk_u8_f32 v158, v160, 3, v137
	v_cvt_pk_u8_f32 v137, v138, 0, 0
	v_max_f32_e32 v159, 1.0, v159
	v_fma_f32 v161, v161, s9, 0.5
	v_cvt_pk_u8_f32 v137, v155, 1, v137
	v_max_f32_e32 v161, 1.0, v161
	v_cvt_pk_u8_f32 v137, v159, 2, v137
	v_cvt_pk_u8_f32 v159, v161, 3, v137
	v_mul_f32_e32 v137, 0xbcb8aa3b, v56
	v_permlane16_swap_b32_e32 v156, v158
	s_nop 0
	v_permlane16_swap_b32_e32 v157, v159
	v_mul_f32_e32 v139, 0xbcb8aa3b, v57
	v_exp_f32_e32 v137, v137
	global_store_dwordx4 v[134:135], v[156:159], off
	s_nop 0
	v_mul_f32_e32 v138, 0xbcb8aa3b, v52
	v_mul_f32_e32 v156, 0xbcb8aa3b, v58
	v_exp_f32_e32 v139, v139
	v_mul_f32_e32 v158, 0xbcb8aa3b, v59
	v_mul_f32_e32 v155, 0xbcb8aa3b, v53
	v_exp_f32_e32 v156, v156
	v_exp_f32_e32 v138, v138
	v_mul_f32_e32 v157, 0xbcb8aa3b, v54
	v_exp_f32_e32 v158, v158
	v_add_f32_e32 v137, 1.0, v137
	v_exp_f32_e32 v155, v155
	v_mul_f32_e32 v159, 0xbcb8aa3b, v55
	v_rcp_f32_e32 v137, v137
	v_add_f32_e32 v139, 1.0, v139
	v_exp_f32_e32 v157, v157
	v_rcp_f32_e32 v139, v139
	v_add_f32_e32 v156, 1.0, v156
	v_exp_f32_e32 v159, v159
	v_add_f32_e32 v138, 1.0, v138
	v_rcp_f32_e32 v156, v156
	v_add_f32_e32 v158, 1.0, v158
	v_rcp_f32_e32 v138, v138
	v_add_f32_e32 v155, 1.0, v155
	v_rcp_f32_e32 v158, v158
	v_fma_f32 v137, v137, s9, 0.5
	v_rcp_f32_e32 v155, v155
	v_add_f32_e32 v157, 1.0, v157
	v_max_f32_e32 v137, 1.0, v137
	v_fma_f32 v139, v139, s9, 0.5
	v_rcp_f32_e32 v157, v157
	v_add_f32_e32 v159, 1.0, v159
	v_max_f32_e32 v139, 1.0, v139
	v_fma_f32 v156, v156, s9, 0.5
	v_rcp_f32_e32 v159, v159
	v_cvt_pk_u8_f32 v137, v137, 0, 0
	v_fma_f32 v138, v138, s9, 0.5
	v_max_f32_e32 v156, 1.0, v156
	v_fma_f32 v158, v158, s9, 0.5
	v_cvt_pk_u8_f32 v137, v139, 1, v137
	v_max_f32_e32 v138, 1.0, v138
	v_fma_f32 v155, v155, s9, 0.5
	v_max_f32_e32 v158, 1.0, v158
	v_cvt_pk_u8_f32 v137, v156, 2, v137
	v_max_f32_e32 v155, 1.0, v155
	v_fma_f32 v157, v157, s9, 0.5
	v_cvt_pk_u8_f32 v156, v158, 3, v137
	v_cvt_pk_u8_f32 v137, v138, 0, 0
	v_max_f32_e32 v157, 1.0, v157
	v_fma_f32 v159, v159, s9, 0.5
	v_cvt_pk_u8_f32 v137, v155, 1, v137
	v_max_f32_e32 v159, 1.0, v159
	v_cvt_pk_u8_f32 v137, v157, 2, v137
	v_cvt_pk_u8_f32 v157, v159, 3, v137
	v_mul_f32_e32 v137, 0xbcb8aa3b, v40
	v_mul_f32_e32 v139, 0xbcb8aa3b, v41
	v_exp_f32_e32 v137, v137
	v_mul_f32_e32 v158, 0xbcb8aa3b, v42
	v_mul_f32_e32 v138, 0xbcb8aa3b, v36
	v_exp_f32_e32 v139, v139
	v_mul_f32_e32 v160, 0xbcb8aa3b, v43
	v_mul_f32_e32 v155, 0xbcb8aa3b, v37
	v_exp_f32_e32 v158, v158
	v_exp_f32_e32 v138, v138
	v_mul_f32_e32 v159, 0xbcb8aa3b, v38
	v_exp_f32_e32 v160, v160
	v_add_f32_e32 v137, 1.0, v137
	v_exp_f32_e32 v155, v155
	v_mul_f32_e32 v161, 0xbcb8aa3b, v39
	v_rcp_f32_e32 v137, v137
	v_add_f32_e32 v139, 1.0, v139
	v_exp_f32_e32 v159, v159
	v_rcp_f32_e32 v139, v139
	v_add_f32_e32 v158, 1.0, v158
	v_exp_f32_e32 v161, v161
	v_add_f32_e32 v138, 1.0, v138
	v_rcp_f32_e32 v158, v158
	v_add_f32_e32 v160, 1.0, v160
	v_rcp_f32_e32 v138, v138
	v_add_f32_e32 v155, 1.0, v155
	v_rcp_f32_e32 v160, v160
	v_fma_f32 v137, v137, s9, 0.5
	v_rcp_f32_e32 v155, v155
	v_add_f32_e32 v159, 1.0, v159
	v_max_f32_e32 v137, 1.0, v137
	v_fma_f32 v139, v139, s9, 0.5
	v_rcp_f32_e32 v159, v159
	v_add_f32_e32 v161, 1.0, v161
	v_max_f32_e32 v139, 1.0, v139
	v_fma_f32 v158, v158, s9, 0.5
	v_rcp_f32_e32 v161, v161
	v_cvt_pk_u8_f32 v137, v137, 0, 0
	v_fma_f32 v138, v138, s9, 0.5
	v_max_f32_e32 v158, 1.0, v158
	v_fma_f32 v160, v160, s9, 0.5
	v_cvt_pk_u8_f32 v137, v139, 1, v137
	v_max_f32_e32 v138, 1.0, v138
	v_fma_f32 v155, v155, s9, 0.5
	v_max_f32_e32 v160, 1.0, v160
	v_cvt_pk_u8_f32 v137, v158, 2, v137
	v_max_f32_e32 v155, 1.0, v155
	v_fma_f32 v159, v159, s9, 0.5
	v_cvt_pk_u8_f32 v158, v160, 3, v137
	v_cvt_pk_u8_f32 v137, v138, 0, 0
	v_max_f32_e32 v159, 1.0, v159
	v_fma_f32 v161, v161, s9, 0.5
	v_cvt_pk_u8_f32 v137, v155, 1, v137
	v_max_f32_e32 v161, 1.0, v161
	v_cvt_pk_u8_f32 v137, v159, 2, v137
	v_cvt_pk_u8_f32 v159, v161, 3, v137
	v_permlane16_swap_b32_e32 v156, v158
	s_nop 0
	v_permlane16_swap_b32_e32 v157, v159
	global_store_dwordx4 v[134:135], v[156:159], off offset:128
	v_mul_f32_e32 v134, 0xbcb8aa3b, v30
	v_mul_f32_e32 v135, 0xbcb8aa3b, v26
	v_add_u32_e32 v136, 0xa0, v136
	v_mad_i64_i32 v[132:133], s[6:7], v136, s8, v[132:133]
	v_mul_f32_e32 v136, 0xbcb8aa3b, v31
	v_mul_f32_e32 v137, 0xbcb8aa3b, v27
	v_exp_f32_e32 v134, v134
	v_exp_f32_e32 v135, v135
	v_mul_f32_e32 v138, 0xbcb8aa3b, v32
	v_mul_f32_e32 v139, 0xbcb8aa3b, v28
	v_exp_f32_e32 v136, v136
	v_exp_f32_e32 v137, v137
	v_mul_f32_e32 v155, 0xbcb8aa3b, v33
	v_mul_f32_e32 v156, 0xbcb8aa3b, v29
	v_exp_f32_e32 v138, v138
	v_exp_f32_e32 v139, v139
	v_exp_f32_e32 v155, v155
	v_exp_f32_e32 v156, v156
	v_add_f32_e32 v134, 1.0, v134
	v_add_f32_e32 v135, 1.0, v135
	v_rcp_f32_e32 v134, v134
	v_rcp_f32_e32 v135, v135
	v_add_f32_e32 v136, 1.0, v136
	v_add_f32_e32 v137, 1.0, v137
	v_rcp_f32_e32 v136, v136
	v_rcp_f32_e32 v137, v137
	v_add_f32_e32 v138, 1.0, v138
	v_add_f32_e32 v139, 1.0, v139
	v_rcp_f32_e32 v138, v138
	v_rcp_f32_e32 v139, v139
	v_add_f32_e32 v155, 1.0, v155
	v_add_f32_e32 v156, 1.0, v156
	v_rcp_f32_e32 v155, v155
	v_rcp_f32_e32 v156, v156
	v_fma_f32 v134, v134, s9, 0.5
	v_fma_f32 v135, v135, s9, 0.5
	v_max_f32_e32 v134, 1.0, v134
	v_max_f32_e32 v135, 1.0, v135
	v_fma_f32 v136, v136, s9, 0.5
	v_fma_f32 v137, v137, s9, 0.5
	v_max_f32_e32 v136, 1.0, v136
	v_max_f32_e32 v137, 1.0, v137
	v_fma_f32 v138, v138, s9, 0.5
	v_fma_f32 v139, v139, s9, 0.5
	v_cvt_pk_u8_f32 v134, v134, 0, 0
	v_cvt_pk_u8_f32 v135, v135, 0, 0
	v_max_f32_e32 v138, 1.0, v138
	v_max_f32_e32 v139, 1.0, v139
	v_fma_f32 v155, v155, s9, 0.5
	v_fma_f32 v156, v156, s9, 0.5
	v_cvt_pk_u8_f32 v134, v136, 1, v134
	v_cvt_pk_u8_f32 v135, v137, 1, v135
	v_max_f32_e32 v155, 1.0, v155
	v_max_f32_e32 v156, 1.0, v156
	v_cvt_pk_u8_f32 v134, v138, 2, v134
	v_cvt_pk_u8_f32 v135, v139, 2, v135
	v_cvt_pk_u8_f32 v134, v155, 3, v134
	v_cvt_pk_u8_f32 v135, v156, 3, v135
	v_mul_f32_e32 v136, 0xbcb8aa3b, v14
	v_mul_f32_e32 v137, 0xbcb8aa3b, v10
	v_mul_f32_e32 v138, 0xbcb8aa3b, v15
	v_mul_f32_e32 v139, 0xbcb8aa3b, v11
	v_exp_f32_e32 v136, v136
	v_exp_f32_e32 v137, v137
	v_mul_f32_e32 v155, 0xbcb8aa3b, v16
	v_mul_f32_e32 v156, 0xbcb8aa3b, v12
	v_exp_f32_e32 v138, v138
	v_exp_f32_e32 v139, v139
	v_mul_f32_e32 v157, 0xbcb8aa3b, v17
	v_mul_f32_e32 v158, 0xbcb8aa3b, v13
	v_exp_f32_e32 v155, v155
	v_exp_f32_e32 v156, v156
	v_exp_f32_e32 v157, v157
	v_exp_f32_e32 v158, v158
	v_add_f32_e32 v136, 1.0, v136
	v_add_f32_e32 v137, 1.0, v137
	v_rcp_f32_e32 v136, v136
	v_rcp_f32_e32 v137, v137
	v_add_f32_e32 v138, 1.0, v138
	v_add_f32_e32 v139, 1.0, v139
	v_rcp_f32_e32 v138, v138
	v_rcp_f32_e32 v139, v139
	v_add_f32_e32 v155, 1.0, v155
	v_add_f32_e32 v156, 1.0, v156
	v_rcp_f32_e32 v155, v155
	v_rcp_f32_e32 v156, v156
	v_add_f32_e32 v157, 1.0, v157
	v_add_f32_e32 v158, 1.0, v158
	v_rcp_f32_e32 v157, v157
	v_rcp_f32_e32 v158, v158
	v_fma_f32 v136, v136, s9, 0.5
	v_fma_f32 v137, v137, s9, 0.5
	v_max_f32_e32 v136, 1.0, v136
	v_max_f32_e32 v137, 1.0, v137
	v_fma_f32 v138, v138, s9, 0.5
	v_fma_f32 v139, v139, s9, 0.5
	v_max_f32_e32 v138, 1.0, v138
	v_max_f32_e32 v139, 1.0, v139
	v_fma_f32 v155, v155, s9, 0.5
	v_fma_f32 v156, v156, s9, 0.5
	v_cvt_pk_u8_f32 v136, v136, 0, 0
	v_cvt_pk_u8_f32 v137, v137, 0, 0
	v_max_f32_e32 v155, 1.0, v155
	v_max_f32_e32 v156, 1.0, v156
	v_fma_f32 v157, v157, s9, 0.5
	v_fma_f32 v158, v158, s9, 0.5
	v_cvt_pk_u8_f32 v136, v138, 1, v136
	v_cvt_pk_u8_f32 v137, v139, 1, v137
	v_max_f32_e32 v157, 1.0, v157
	v_max_f32_e32 v158, 1.0, v158
	v_cvt_pk_u8_f32 v136, v155, 2, v136
	v_cvt_pk_u8_f32 v137, v156, 2, v137
	v_cvt_pk_u8_f32 v136, v157, 3, v136
	v_cvt_pk_u8_f32 v137, v158, 3, v137
	v_mul_f32_e32 v138, 0xbcb8aa3b, v22
	v_mul_f32_e32 v139, 0xbcb8aa3b, v18
	s_nop 0
	s_nop 0
	v_exp_f32_e32 v138, v138
	v_exp_f32_e32 v139, v139
	v_permlane16_swap_b32_e32 v134, v136
	v_add_f32_e32 v138, 1.0, v138
	v_add_f32_e32 v139, 1.0, v139
	v_rcp_f32_e32 v138, v138
	v_rcp_f32_e32 v139, v139
	v_permlane16_swap_b32_e32 v135, v137
	global_store_dwordx4 v[132:133], v[134:137], off
	v_mul_f32_e32 v155, 0x3c800000, v25
	v_mul_f32_e32 v156, 0x3c800000, v21
	v_mul_f32_e32 v136, 0xbcb8aa3b, v23
	v_mul_f32_e32 v137, 0xbcb8aa3b, v19
	v_fma_f32 v134, v138, s9, 0.5
	v_fma_f32 v135, v139, s9, 0.5
	v_mul_f32_e32 v138, 0xbcb8aa3b, v24
	v_mul_f32_e32 v139, 0xbcb8aa3b, v20
	v_exp_f32_e32 v136, v136
	v_exp_f32_e32 v137, v137
	v_exp_f32_e32 v138, v138
	v_exp_f32_e32 v139, v139
	v_mul_f32_e32 v155, 0xbfb8aa3b, v155
	v_mul_f32_e32 v156, 0xbfb8aa3b, v156
	v_exp_f32_e32 v155, v155
	v_exp_f32_e32 v156, v156
	v_add_f32_e32 v136, 1.0, v136
	v_add_f32_e32 v137, 1.0, v137
	v_rcp_f32_e32 v136, v136
	v_rcp_f32_e32 v137, v137
	v_add_f32_e32 v138, 1.0, v138
	v_add_f32_e32 v139, 1.0, v139
	v_rcp_f32_e32 v138, v138
	v_rcp_f32_e32 v139, v139
	v_add_f32_e32 v155, 1.0, v155
	v_add_f32_e32 v156, 1.0, v156
	v_rcp_f32_e32 v155, v155
	v_rcp_f32_e32 v156, v156
	v_max_f32_e32 v134, 1.0, v134
	v_max_f32_e32 v135, 1.0, v135
	v_fma_f32 v136, v136, s9, 0.5
	v_fma_f32 v137, v137, s9, 0.5
	v_max_f32_e32 v136, 1.0, v136
	v_max_f32_e32 v137, 1.0, v137
	v_fma_f32 v138, v138, s9, 0.5
	v_fma_f32 v139, v139, s9, 0.5
	v_cvt_pk_u8_f32 v134, v134, 0, 0
	v_cvt_pk_u8_f32 v135, v135, 0, 0
	v_max_f32_e32 v138, 1.0, v138
	v_max_f32_e32 v139, 1.0, v139
	v_fma_f32 v155, v155, s9, 0.5
	v_fma_f32 v156, v156, s9, 0.5
	v_cvt_pk_u8_f32 v134, v136, 1, v134
	v_cvt_pk_u8_f32 v135, v137, 1, v135
	v_max_f32_e32 v155, 1.0, v155
	v_max_f32_e32 v156, 1.0, v156
	v_cvt_pk_u8_f32 v134, v138, 2, v134
	v_cvt_pk_u8_f32 v135, v139, 2, v135
	v_cvt_pk_u8_f32 v134, v155, 3, v134
	v_cvt_pk_u8_f32 v135, v156, 3, v135
	v_mul_f32_e32 v136, 0xbcb8aa3b, v6
	v_mul_f32_e32 v137, 0xbcb8aa3b, v2
	v_mul_f32_e32 v138, 0xbcb8aa3b, v7
	v_mul_f32_e32 v139, 0xbcb8aa3b, v3
	v_exp_f32_e32 v136, v136
	v_exp_f32_e32 v137, v137
	v_mul_f32_e32 v155, 0xbcb8aa3b, v8
	v_mul_f32_e32 v156, 0xbcb8aa3b, v4
	v_exp_f32_e32 v138, v138
	v_exp_f32_e32 v139, v139
	v_mul_f32_e32 v157, 0xbcb8aa3b, v9
	v_mul_f32_e32 v158, 0xbcb8aa3b, v5
	v_exp_f32_e32 v155, v155
	v_exp_f32_e32 v156, v156
	v_exp_f32_e32 v157, v157
	v_exp_f32_e32 v158, v158
	v_add_f32_e32 v136, 1.0, v136
	v_add_f32_e32 v137, 1.0, v137
	v_rcp_f32_e32 v136, v136
	v_rcp_f32_e32 v137, v137
	v_add_f32_e32 v138, 1.0, v138
	v_add_f32_e32 v139, 1.0, v139
	v_rcp_f32_e32 v138, v138
	v_rcp_f32_e32 v139, v139
	v_add_f32_e32 v155, 1.0, v155
	v_add_f32_e32 v156, 1.0, v156
	v_rcp_f32_e32 v155, v155
	v_rcp_f32_e32 v156, v156
	v_add_f32_e32 v157, 1.0, v157
	v_add_f32_e32 v158, 1.0, v158
	v_rcp_f32_e32 v157, v157
	v_rcp_f32_e32 v158, v158
	v_fma_f32 v136, v136, s9, 0.5
	v_fma_f32 v137, v137, s9, 0.5
	v_max_f32_e32 v136, 1.0, v136
	v_max_f32_e32 v137, 1.0, v137
	v_fma_f32 v138, v138, s9, 0.5
	v_fma_f32 v139, v139, s9, 0.5
	v_max_f32_e32 v138, 1.0, v138
	v_max_f32_e32 v139, 1.0, v139
	v_fma_f32 v155, v155, s9, 0.5
	v_fma_f32 v156, v156, s9, 0.5
	v_cvt_pk_u8_f32 v136, v136, 0, 0
	v_cvt_pk_u8_f32 v137, v137, 0, 0
	v_max_f32_e32 v155, 1.0, v155
	v_max_f32_e32 v156, 1.0, v156
	v_fma_f32 v157, v157, s9, 0.5
	v_fma_f32 v158, v158, s9, 0.5
	v_cvt_pk_u8_f32 v136, v138, 1, v136
	v_cvt_pk_u8_f32 v137, v139, 1, v137
	v_max_f32_e32 v157, 1.0, v157
	v_max_f32_e32 v158, 1.0, v158
	v_cvt_pk_u8_f32 v136, v155, 2, v136
	v_cvt_pk_u8_f32 v137, v156, 2, v137
	v_cvt_pk_u8_f32 v136, v157, 3, v136
	v_cvt_pk_u8_f32 v137, v158, 3, v137
	s_nop 0
	v_permlane16_swap_b32_e32 v134, v136
	v_permlane16_swap_b32_e32 v135, v137
	global_store_dwordx4 v[132:133], v[134:137], off offset:128

.LBB0_219:
	s_andn2_b64 vcc, exec, s[6:7]
	s_cbranch_vccnz .LBB0_221
	v_mul_f32_e32 v4, 0xbcb8aa3b, v160
	v_mul_f32_e32 v9, 0xbcb8aa3b, v161
	v_exp_f32_e32 v4, v4
	v_mul_f32_e32 v12, 0xbcb8aa3b, v162
	v_mul_f32_e32 v5, 0xbcb8aa3b, v156
	v_exp_f32_e32 v9, v9
	v_mul_f32_e32 v14, 0xbcb8aa3b, v163
	v_mul_f32_e32 v11, 0xbcb8aa3b, v157
	v_exp_f32_e32 v12, v12
	v_exp_f32_e32 v5, v5
	v_mul_f32_e32 v13, 0xbcb8aa3b, v158
	v_exp_f32_e32 v14, v14
	v_add_f32_e32 v4, 1.0, v4
	v_exp_f32_e32 v11, v11
	v_mul_f32_e32 v15, 0xbcb8aa3b, v159
	v_rcp_f32_e32 v7, v4
	v_add_f32_e32 v9, 1.0, v9
	v_exp_f32_e32 v13, v13
	v_rcp_f32_e32 v9, v9
	v_add_f32_e32 v12, 1.0, v12
	v_exp_f32_e32 v15, v15
	v_add_f32_e32 v4, 1.0, v5
	v_rcp_f32_e32 v12, v12
	v_add_f32_e32 v14, 1.0, v14
	v_rcp_f32_e32 v8, v4
	s_mov_b32 s9, 0x437f0000
	v_add_f32_e32 v11, 1.0, v11
	v_rcp_f32_e32 v14, v14
	v_fma_f32 v7, v7, s9, 0.5
	v_rcp_f32_e32 v11, v11
	v_add_f32_e32 v13, 1.0, v13
	v_or_b32_e32 v2, 0xffffb800, v195
	v_max_f32_e32 v7, 1.0, v7
	v_fma_f32 v9, v9, s9, 0.5
	v_rcp_f32_e32 v13, v13
	v_add_f32_e32 v15, 1.0, v15
	v_lshl_add_u32 v2, s74, 8, v2
	v_max_f32_e32 v9, 1.0, v9
	v_fma_f32 v12, v12, s9, 0.5
	v_rcp_f32_e32 v15, v15
	v_cvt_pk_u8_f32 v7, v7, 0, 0
	v_fma_f32 v8, v8, s9, 0.5
	v_bfe_u32 v3, v2, 3, 1
	v_max_f32_e32 v12, 1.0, v12
	v_fma_f32 v14, v14, s9, 0.5
	v_cvt_pk_u8_f32 v7, v9, 1, v7
	v_lshl_or_b32 v6, v3, 4, v10
	v_lshlrev_b32_e32 v3, 3, v3
	v_max_f32_e32 v8, 1.0, v8
	v_fma_f32 v11, v11, s9, 0.5
	v_max_f32_e32 v14, 1.0, v14
	v_cvt_pk_u8_f32 v7, v12, 2, v7
	v_sub_u32_e32 v2, v2, v3
	v_max_f32_e32 v11, 1.0, v11
	v_fma_f32 v13, v13, s9, 0.5
	v_cvt_pk_u8_f32 v12, v14, 3, v7
	v_cvt_pk_u8_f32 v7, v8, 0, 0
	v_ashrrev_i32_e32 v3, 31, v2
	v_max_f32_e32 v13, 1.0, v13
	v_fma_f32 v15, v15, s9, 0.5
	v_cvt_pk_u8_f32 v7, v11, 1, v7
	v_lshl_add_u64 v[2:3], s[58:59], 0, v[2:3]
	s_movk_i32 s8, 0x3000
	v_max_f32_e32 v15, 1.0, v15
	v_cvt_pk_u8_f32 v7, v13, 2, v7
	v_mad_i64_i32 v[4:5], s[6:7], v6, s8, v[2:3]
	v_cvt_pk_u8_f32 v13, v15, 3, v7
	v_mul_f32_e32 v7, 0xbcb8aa3b, v144
	v_mul_f32_e32 v9, 0xbcb8aa3b, v145
	v_exp_f32_e32 v7, v7
	v_mul_f32_e32 v14, 0xbcb8aa3b, v146
	v_mul_f32_e32 v8, 0xbcb8aa3b, v140
	v_exp_f32_e32 v9, v9
	v_mul_f32_e32 v16, 0xbcb8aa3b, v147
	v_mul_f32_e32 v11, 0xbcb8aa3b, v141
	v_exp_f32_e32 v14, v14
	v_exp_f32_e32 v8, v8
	v_mul_f32_e32 v15, 0xbcb8aa3b, v142
	v_exp_f32_e32 v16, v16
	v_add_f32_e32 v7, 1.0, v7
	v_exp_f32_e32 v11, v11
	v_mul_f32_e32 v17, 0xbcb8aa3b, v143
	v_rcp_f32_e32 v7, v7
	v_add_f32_e32 v9, 1.0, v9
	v_exp_f32_e32 v15, v15
	v_rcp_f32_e32 v9, v9
	v_add_f32_e32 v14, 1.0, v14
	v_exp_f32_e32 v17, v17
	v_add_f32_e32 v8, 1.0, v8
	v_rcp_f32_e32 v14, v14
	v_add_f32_e32 v16, 1.0, v16
	v_rcp_f32_e32 v8, v8
	v_add_f32_e32 v11, 1.0, v11
	v_rcp_f32_e32 v16, v16
	v_fma_f32 v7, v7, s9, 0.5
	v_rcp_f32_e32 v11, v11
	v_add_f32_e32 v15, 1.0, v15
	v_max_f32_e32 v7, 1.0, v7
	v_fma_f32 v9, v9, s9, 0.5
	v_rcp_f32_e32 v15, v15
	v_add_f32_e32 v17, 1.0, v17
	v_max_f32_e32 v9, 1.0, v9
	v_fma_f32 v14, v14, s9, 0.5
	v_rcp_f32_e32 v17, v17
	v_cvt_pk_u8_f32 v7, v7, 0, 0
	v_fma_f32 v8, v8, s9, 0.5
	v_max_f32_e32 v14, 1.0, v14
	v_fma_f32 v16, v16, s9, 0.5
	v_cvt_pk_u8_f32 v7, v9, 1, v7
	v_max_f32_e32 v8, 1.0, v8
	v_fma_f32 v11, v11, s9, 0.5
	v_max_f32_e32 v16, 1.0, v16
	v_cvt_pk_u8_f32 v7, v14, 2, v7
	v_max_f32_e32 v11, 1.0, v11
	v_fma_f32 v15, v15, s9, 0.5
	v_cvt_pk_u8_f32 v14, v16, 3, v7
	v_cvt_pk_u8_f32 v7, v8, 0, 0
	v_max_f32_e32 v15, 1.0, v15
	v_fma_f32 v17, v17, s9, 0.5
	v_cvt_pk_u8_f32 v7, v11, 1, v7
	v_max_f32_e32 v17, 1.0, v17
	v_cvt_pk_u8_f32 v7, v15, 2, v7
	v_cvt_pk_u8_f32 v15, v17, 3, v7
	v_mul_f32_e32 v7, 0xbcb8aa3b, v152
	v_permlane16_swap_b32_e32 v12, v14
	s_nop 0
	v_permlane16_swap_b32_e32 v13, v15
	v_mul_f32_e32 v9, 0xbcb8aa3b, v153
	v_exp_f32_e32 v7, v7
	global_store_dwordx4 v[4:5], v[12:15], off
	s_nop 0
	v_mul_f32_e32 v8, 0xbcb8aa3b, v148
	v_mul_f32_e32 v12, 0xbcb8aa3b, v154
	v_exp_f32_e32 v9, v9
	v_mul_f32_e32 v14, 0xbcb8aa3b, v155
	v_mul_f32_e32 v11, 0xbcb8aa3b, v149
	v_exp_f32_e32 v12, v12
	v_exp_f32_e32 v8, v8
	v_mul_f32_e32 v13, 0xbcb8aa3b, v150
	v_exp_f32_e32 v14, v14
	v_add_f32_e32 v7, 1.0, v7
	v_exp_f32_e32 v11, v11
	v_mul_f32_e32 v15, 0xbcb8aa3b, v151
	v_rcp_f32_e32 v7, v7
	v_add_f32_e32 v9, 1.0, v9
	v_exp_f32_e32 v13, v13
	v_rcp_f32_e32 v9, v9
	v_add_f32_e32 v12, 1.0, v12
	v_exp_f32_e32 v15, v15
	v_add_f32_e32 v8, 1.0, v8
	v_rcp_f32_e32 v12, v12
	v_add_f32_e32 v14, 1.0, v14
	v_rcp_f32_e32 v8, v8
	v_add_f32_e32 v11, 1.0, v11
	v_rcp_f32_e32 v14, v14
	v_fma_f32 v7, v7, s9, 0.5
	v_rcp_f32_e32 v11, v11
	v_add_f32_e32 v13, 1.0, v13
	v_max_f32_e32 v7, 1.0, v7
	v_fma_f32 v9, v9, s9, 0.5
	v_rcp_f32_e32 v13, v13
	v_add_f32_e32 v15, 1.0, v15
	v_max_f32_e32 v9, 1.0, v9
	v_fma_f32 v12, v12, s9, 0.5
	v_rcp_f32_e32 v15, v15
	v_cvt_pk_u8_f32 v7, v7, 0, 0
	v_fma_f32 v8, v8, s9, 0.5
	v_max_f32_e32 v12, 1.0, v12
	v_fma_f32 v14, v14, s9, 0.5
	v_cvt_pk_u8_f32 v7, v9, 1, v7
	v_max_f32_e32 v8, 1.0, v8
	v_fma_f32 v11, v11, s9, 0.5
	v_max_f32_e32 v14, 1.0, v14
	v_cvt_pk_u8_f32 v7, v12, 2, v7
	v_max_f32_e32 v11, 1.0, v11
	v_fma_f32 v13, v13, s9, 0.5
	v_cvt_pk_u8_f32 v12, v14, 3, v7
	v_cvt_pk_u8_f32 v7, v8, 0, 0
	v_max_f32_e32 v13, 1.0, v13
	v_fma_f32 v15, v15, s9, 0.5
	v_cvt_pk_u8_f32 v7, v11, 1, v7
	v_max_f32_e32 v15, 1.0, v15
	v_cvt_pk_u8_f32 v7, v13, 2, v7
	v_cvt_pk_u8_f32 v13, v15, 3, v7
	v_mul_f32_e32 v7, 0xbcb8aa3b, v136
	v_mul_f32_e32 v9, 0xbcb8aa3b, v137
	v_exp_f32_e32 v7, v7
	v_mul_f32_e32 v14, 0xbcb8aa3b, v138
	v_mul_f32_e32 v8, 0xbcb8aa3b, v132
	v_exp_f32_e32 v9, v9
	v_mul_f32_e32 v16, 0xbcb8aa3b, v139
	v_mul_f32_e32 v11, 0xbcb8aa3b, v133
	v_exp_f32_e32 v14, v14
	v_exp_f32_e32 v8, v8
	v_mul_f32_e32 v15, 0xbcb8aa3b, v134
	v_exp_f32_e32 v16, v16
	v_add_f32_e32 v7, 1.0, v7
	v_exp_f32_e32 v11, v11
	v_mul_f32_e32 v17, 0xbcb8aa3b, v135
	v_rcp_f32_e32 v7, v7
	v_add_f32_e32 v9, 1.0, v9
	v_exp_f32_e32 v15, v15
	v_rcp_f32_e32 v9, v9
	v_add_f32_e32 v14, 1.0, v14
	v_exp_f32_e32 v17, v17
	v_add_f32_e32 v8, 1.0, v8
	v_rcp_f32_e32 v14, v14
	v_add_f32_e32 v16, 1.0, v16
	v_rcp_f32_e32 v8, v8
	v_add_f32_e32 v11, 1.0, v11
	v_rcp_f32_e32 v16, v16
	v_fma_f32 v7, v7, s9, 0.5
	v_rcp_f32_e32 v11, v11
	v_add_f32_e32 v15, 1.0, v15
	v_max_f32_e32 v7, 1.0, v7
	v_fma_f32 v9, v9, s9, 0.5
	v_rcp_f32_e32 v15, v15
	v_add_f32_e32 v17, 1.0, v17
	v_max_f32_e32 v9, 1.0, v9
	v_fma_f32 v14, v14, s9, 0.5
	v_rcp_f32_e32 v17, v17
	v_cvt_pk_u8_f32 v7, v7, 0, 0
	v_fma_f32 v8, v8, s9, 0.5
	v_max_f32_e32 v14, 1.0, v14
	v_fma_f32 v16, v16, s9, 0.5
	v_cvt_pk_u8_f32 v7, v9, 1, v7
	v_max_f32_e32 v8, 1.0, v8
	v_fma_f32 v11, v11, s9, 0.5
	v_max_f32_e32 v16, 1.0, v16
	v_cvt_pk_u8_f32 v7, v14, 2, v7
	v_max_f32_e32 v11, 1.0, v11
	v_fma_f32 v15, v15, s9, 0.5
	v_cvt_pk_u8_f32 v14, v16, 3, v7
	v_cvt_pk_u8_f32 v7, v8, 0, 0
	v_max_f32_e32 v15, 1.0, v15
	v_fma_f32 v17, v17, s9, 0.5
	v_cvt_pk_u8_f32 v7, v11, 1, v7
	v_max_f32_e32 v17, 1.0, v17
	v_cvt_pk_u8_f32 v7, v15, 2, v7
	v_cvt_pk_u8_f32 v15, v17, 3, v7
	v_permlane16_swap_b32_e32 v12, v14
	s_nop 0
	v_permlane16_swap_b32_e32 v13, v15
	global_store_dwordx4 v[4:5], v[12:15], off offset:128
	v_mul_f32_e32 v4, 0xbcb8aa3b, v128
	s_nop 0
	v_mul_f32_e32 v5, 0xbcb8aa3b, v124
	v_exp_f32_e32 v4, v4
	v_exp_f32_e32 v5, v5
	v_or_b32_e32 v7, 32, v6
	v_add_f32_e32 v4, 1.0, v4
	v_rcp_f32_e32 v8, v4
	v_add_f32_e32 v4, 1.0, v5
	v_rcp_f32_e32 v9, v4
	v_mad_i64_i32 v[4:5], s[6:7], v7, s8, v[2:3]
	v_fma_f32 v7, v8, s9, 0.5
	v_fma_f32 v8, v9, s9, 0.5
	v_mul_f32_e32 v9, 0xbcb8aa3b, v129
	v_mul_f32_e32 v12, 0xbcb8aa3b, v130
	v_exp_f32_e32 v9, v9
	v_mul_f32_e32 v14, 0xbcb8aa3b, v131
	v_mul_f32_e32 v11, 0xbcb8aa3b, v125
	v_exp_f32_e32 v12, v12
	v_mul_f32_e32 v13, 0xbcb8aa3b, v126
	v_exp_f32_e32 v14, v14
	v_exp_f32_e32 v11, v11
	v_mul_f32_e32 v15, 0xbcb8aa3b, v127
	v_add_f32_e32 v9, 1.0, v9
	v_exp_f32_e32 v13, v13
	v_rcp_f32_e32 v9, v9
	v_add_f32_e32 v12, 1.0, v12
	v_exp_f32_e32 v15, v15
	v_rcp_f32_e32 v12, v12
	v_add_f32_e32 v14, 1.0, v14
	v_add_f32_e32 v11, 1.0, v11
	v_rcp_f32_e32 v14, v14
	v_rcp_f32_e32 v11, v11
	v_add_f32_e32 v13, 1.0, v13
	v_max_f32_e32 v7, 1.0, v7
	v_fma_f32 v9, v9, s9, 0.5
	v_rcp_f32_e32 v13, v13
	v_add_f32_e32 v15, 1.0, v15
	v_max_f32_e32 v9, 1.0, v9
	v_fma_f32 v12, v12, s9, 0.5
	v_rcp_f32_e32 v15, v15
	v_cvt_pk_u8_f32 v7, v7, 0, 0
	v_max_f32_e32 v12, 1.0, v12
	v_fma_f32 v14, v14, s9, 0.5
	v_cvt_pk_u8_f32 v7, v9, 1, v7
	v_max_f32_e32 v8, 1.0, v8
	v_fma_f32 v11, v11, s9, 0.5
	v_max_f32_e32 v14, 1.0, v14
	v_cvt_pk_u8_f32 v7, v12, 2, v7
	v_max_f32_e32 v11, 1.0, v11
	v_fma_f32 v13, v13, s9, 0.5
	v_cvt_pk_u8_f32 v12, v14, 3, v7
	v_cvt_pk_u8_f32 v7, v8, 0, 0
	v_max_f32_e32 v13, 1.0, v13
	v_fma_f32 v15, v15, s9, 0.5
	v_cvt_pk_u8_f32 v7, v11, 1, v7
	v_max_f32_e32 v15, 1.0, v15
	v_cvt_pk_u8_f32 v7, v13, 2, v7
	v_cvt_pk_u8_f32 v13, v15, 3, v7
	v_mul_f32_e32 v7, 0xbcb8aa3b, v112
	v_mul_f32_e32 v9, 0xbcb8aa3b, v113
	v_exp_f32_e32 v7, v7
	v_mul_f32_e32 v14, 0xbcb8aa3b, v114
	v_mul_f32_e32 v8, 0xbcb8aa3b, v108
	v_exp_f32_e32 v9, v9
	v_mul_f32_e32 v16, 0xbcb8aa3b, v115
	v_mul_f32_e32 v11, 0xbcb8aa3b, v109
	v_exp_f32_e32 v14, v14
	v_exp_f32_e32 v8, v8
	v_mul_f32_e32 v15, 0xbcb8aa3b, v110
	v_exp_f32_e32 v16, v16
	v_add_f32_e32 v7, 1.0, v7
	v_exp_f32_e32 v11, v11
	v_mul_f32_e32 v17, 0xbcb8aa3b, v111
	v_rcp_f32_e32 v7, v7
	v_add_f32_e32 v9, 1.0, v9
	v_exp_f32_e32 v15, v15
	v_rcp_f32_e32 v9, v9
	v_add_f32_e32 v14, 1.0, v14
	v_exp_f32_e32 v17, v17
	v_add_f32_e32 v8, 1.0, v8
	v_rcp_f32_e32 v14, v14
	v_add_f32_e32 v16, 1.0, v16
	v_rcp_f32_e32 v8, v8
	v_add_f32_e32 v11, 1.0, v11
	v_rcp_f32_e32 v16, v16
	v_fma_f32 v7, v7, s9, 0.5
	v_rcp_f32_e32 v11, v11
	v_add_f32_e32 v15, 1.0, v15
	v_max_f32_e32 v7, 1.0, v7
	v_fma_f32 v9, v9, s9, 0.5
	v_rcp_f32_e32 v15, v15
	v_add_f32_e32 v17, 1.0, v17
	v_max_f32_e32 v9, 1.0, v9
	v_fma_f32 v14, v14, s9, 0.5
	v_rcp_f32_e32 v17, v17
	v_cvt_pk_u8_f32 v7, v7, 0, 0
	v_fma_f32 v8, v8, s9, 0.5
	v_max_f32_e32 v14, 1.0, v14
	v_fma_f32 v16, v16, s9, 0.5
	v_cvt_pk_u8_f32 v7, v9, 1, v7
	v_max_f32_e32 v8, 1.0, v8
	v_fma_f32 v11, v11, s9, 0.5
	v_max_f32_e32 v16, 1.0, v16
	v_cvt_pk_u8_f32 v7, v14, 2, v7
	v_max_f32_e32 v11, 1.0, v11
	v_fma_f32 v15, v15, s9, 0.5
	v_cvt_pk_u8_f32 v14, v16, 3, v7
	v_cvt_pk_u8_f32 v7, v8, 0, 0
	v_max_f32_e32 v15, 1.0, v15
	v_fma_f32 v17, v17, s9, 0.5
	v_cvt_pk_u8_f32 v7, v11, 1, v7
	v_max_f32_e32 v17, 1.0, v17
	v_cvt_pk_u8_f32 v7, v15, 2, v7
	v_cvt_pk_u8_f32 v15, v17, 3, v7
	v_mul_f32_e32 v7, 0xbcb8aa3b, v120
	v_permlane16_swap_b32_e32 v12, v14
	s_nop 0
	v_permlane16_swap_b32_e32 v13, v15
	v_mul_f32_e32 v9, 0xbcb8aa3b, v121
	v_exp_f32_e32 v7, v7
	global_store_dwordx4 v[4:5], v[12:15], off
	s_nop 0
	v_mul_f32_e32 v8, 0xbcb8aa3b, v116
	v_mul_f32_e32 v12, 0xbcb8aa3b, v122
	v_exp_f32_e32 v9, v9
	v_mul_f32_e32 v14, 0xbcb8aa3b, v123
	v_mul_f32_e32 v11, 0xbcb8aa3b, v117
	v_exp_f32_e32 v12, v12
	v_exp_f32_e32 v8, v8
	v_mul_f32_e32 v13, 0xbcb8aa3b, v118
	v_exp_f32_e32 v14, v14
	v_add_f32_e32 v7, 1.0, v7
	v_exp_f32_e32 v11, v11
	v_mul_f32_e32 v15, 0xbcb8aa3b, v119
	v_rcp_f32_e32 v7, v7
	v_add_f32_e32 v9, 1.0, v9
	v_exp_f32_e32 v13, v13
	v_rcp_f32_e32 v9, v9
	v_add_f32_e32 v12, 1.0, v12
	v_exp_f32_e32 v15, v15
	v_add_f32_e32 v8, 1.0, v8
	v_rcp_f32_e32 v12, v12
	v_add_f32_e32 v14, 1.0, v14
	v_rcp_f32_e32 v8, v8
	v_add_f32_e32 v11, 1.0, v11
	v_rcp_f32_e32 v14, v14
	v_fma_f32 v7, v7, s9, 0.5
	v_rcp_f32_e32 v11, v11
	v_add_f32_e32 v13, 1.0, v13
	v_max_f32_e32 v7, 1.0, v7
	v_fma_f32 v9, v9, s9, 0.5
	v_rcp_f32_e32 v13, v13
	v_add_f32_e32 v15, 1.0, v15
	v_max_f32_e32 v9, 1.0, v9
	v_fma_f32 v12, v12, s9, 0.5
	v_rcp_f32_e32 v15, v15
	v_cvt_pk_u8_f32 v7, v7, 0, 0
	v_fma_f32 v8, v8, s9, 0.5
	v_max_f32_e32 v12, 1.0, v12
	v_fma_f32 v14, v14, s9, 0.5
	v_cvt_pk_u8_f32 v7, v9, 1, v7
	v_max_f32_e32 v8, 1.0, v8
	v_fma_f32 v11, v11, s9, 0.5
	v_max_f32_e32 v14, 1.0, v14
	v_cvt_pk_u8_f32 v7, v12, 2, v7
	v_max_f32_e32 v11, 1.0, v11
	v_fma_f32 v13, v13, s9, 0.5
	v_cvt_pk_u8_f32 v12, v14, 3, v7
	v_cvt_pk_u8_f32 v7, v8, 0, 0
	v_max_f32_e32 v13, 1.0, v13
	v_fma_f32 v15, v15, s9, 0.5
	v_cvt_pk_u8_f32 v7, v11, 1, v7
	v_max_f32_e32 v15, 1.0, v15
	v_cvt_pk_u8_f32 v7, v13, 2, v7
	v_cvt_pk_u8_f32 v13, v15, 3, v7
	v_mul_f32_e32 v7, 0xbcb8aa3b, v104
	v_mul_f32_e32 v9, 0xbcb8aa3b, v105
	v_exp_f32_e32 v7, v7
	v_mul_f32_e32 v14, 0xbcb8aa3b, v106
	v_mul_f32_e32 v8, 0xbcb8aa3b, v100
	v_exp_f32_e32 v9, v9
	v_mul_f32_e32 v16, 0xbcb8aa3b, v107
	v_mul_f32_e32 v11, 0xbcb8aa3b, v101
	v_exp_f32_e32 v14, v14
	v_exp_f32_e32 v8, v8
	v_mul_f32_e32 v15, 0xbcb8aa3b, v102
	v_exp_f32_e32 v16, v16
	v_add_f32_e32 v7, 1.0, v7
	v_exp_f32_e32 v11, v11
	v_mul_f32_e32 v17, 0xbcb8aa3b, v103
	v_rcp_f32_e32 v7, v7
	v_add_f32_e32 v9, 1.0, v9
	v_exp_f32_e32 v15, v15
	v_rcp_f32_e32 v9, v9
	v_add_f32_e32 v14, 1.0, v14
	v_exp_f32_e32 v17, v17
	v_add_f32_e32 v8, 1.0, v8
	v_rcp_f32_e32 v14, v14
	v_add_f32_e32 v16, 1.0, v16
	v_rcp_f32_e32 v8, v8
	v_add_f32_e32 v11, 1.0, v11
	v_rcp_f32_e32 v16, v16
	v_fma_f32 v7, v7, s9, 0.5
	v_rcp_f32_e32 v11, v11
	v_add_f32_e32 v15, 1.0, v15
	v_max_f32_e32 v7, 1.0, v7
	v_fma_f32 v9, v9, s9, 0.5
	v_rcp_f32_e32 v15, v15
	v_add_f32_e32 v17, 1.0, v17
	v_max_f32_e32 v9, 1.0, v9
	v_fma_f32 v14, v14, s9, 0.5
	v_rcp_f32_e32 v17, v17
	v_cvt_pk_u8_f32 v7, v7, 0, 0
	v_fma_f32 v8, v8, s9, 0.5
	v_max_f32_e32 v14, 1.0, v14
	v_fma_f32 v16, v16, s9, 0.5
	v_cvt_pk_u8_f32 v7, v9, 1, v7
	v_max_f32_e32 v8, 1.0, v8
	v_fma_f32 v11, v11, s9, 0.5
	v_max_f32_e32 v16, 1.0, v16
	v_cvt_pk_u8_f32 v7, v14, 2, v7
	v_max_f32_e32 v11, 1.0, v11
	v_fma_f32 v15, v15, s9, 0.5
	v_cvt_pk_u8_f32 v14, v16, 3, v7
	v_cvt_pk_u8_f32 v7, v8, 0, 0
	v_max_f32_e32 v15, 1.0, v15
	v_fma_f32 v17, v17, s9, 0.5
	v_cvt_pk_u8_f32 v7, v11, 1, v7
	v_max_f32_e32 v17, 1.0, v17
	v_cvt_pk_u8_f32 v7, v15, 2, v7
	v_cvt_pk_u8_f32 v15, v17, 3, v7
	v_permlane16_swap_b32_e32 v12, v14
	s_nop 0
	v_permlane16_swap_b32_e32 v13, v15
	global_store_dwordx4 v[4:5], v[12:15], off offset:128
	v_mul_f32_e32 v4, 0xbcb8aa3b, v96
	s_nop 0
	v_mul_f32_e32 v5, 0xbcb8aa3b, v92
	v_exp_f32_e32 v4, v4
	v_exp_f32_e32 v5, v5
	v_add_u32_e32 v7, 0x80, v6
	v_add_f32_e32 v4, 1.0, v4
	v_rcp_f32_e32 v8, v4
	v_add_f32_e32 v4, 1.0, v5
	v_rcp_f32_e32 v9, v4
	v_mad_i64_i32 v[4:5], s[6:7], v7, s8, v[2:3]
	v_fma_f32 v7, v8, s9, 0.5
	v_fma_f32 v8, v9, s9, 0.5
	v_mul_f32_e32 v9, 0xbcb8aa3b, v97
	v_mul_f32_e32 v12, 0xbcb8aa3b, v98
	v_exp_f32_e32 v9, v9
	v_mul_f32_e32 v14, 0xbcb8aa3b, v99
	v_mul_f32_e32 v11, 0xbcb8aa3b, v93
	v_exp_f32_e32 v12, v12
	v_mul_f32_e32 v13, 0xbcb8aa3b, v94
	v_exp_f32_e32 v14, v14
	v_exp_f32_e32 v11, v11
	v_mul_f32_e32 v15, 0xbcb8aa3b, v95
	v_add_f32_e32 v9, 1.0, v9
	v_exp_f32_e32 v13, v13
	v_rcp_f32_e32 v9, v9
	v_add_f32_e32 v12, 1.0, v12
	v_exp_f32_e32 v15, v15
	v_rcp_f32_e32 v12, v12
	v_add_f32_e32 v14, 1.0, v14
	v_add_f32_e32 v11, 1.0, v11
	v_rcp_f32_e32 v14, v14
	v_rcp_f32_e32 v11, v11
	v_add_f32_e32 v13, 1.0, v13
	v_max_f32_e32 v7, 1.0, v7
	v_fma_f32 v9, v9, s9, 0.5
	v_rcp_f32_e32 v13, v13
	v_add_f32_e32 v15, 1.0, v15
	v_max_f32_e32 v9, 1.0, v9
	v_fma_f32 v12, v12, s9, 0.5
	v_rcp_f32_e32 v15, v15
	v_cvt_pk_u8_f32 v7, v7, 0, 0
	v_max_f32_e32 v12, 1.0, v12
	v_fma_f32 v14, v14, s9, 0.5
	v_cvt_pk_u8_f32 v7, v9, 1, v7
	v_max_f32_e32 v8, 1.0, v8
	v_fma_f32 v11, v11, s9, 0.5
	v_max_f32_e32 v14, 1.0, v14
	v_cvt_pk_u8_f32 v7, v12, 2, v7
	v_max_f32_e32 v11, 1.0, v11
	v_fma_f32 v13, v13, s9, 0.5
	v_cvt_pk_u8_f32 v12, v14, 3, v7
	v_cvt_pk_u8_f32 v7, v8, 0, 0
	v_max_f32_e32 v13, 1.0, v13
	v_fma_f32 v15, v15, s9, 0.5
	v_cvt_pk_u8_f32 v7, v11, 1, v7
	v_max_f32_e32 v15, 1.0, v15
	v_cvt_pk_u8_f32 v7, v13, 2, v7
	v_cvt_pk_u8_f32 v13, v15, 3, v7
	v_mul_f32_e32 v7, 0xbcb8aa3b, v80
	v_mul_f32_e32 v9, 0xbcb8aa3b, v81
	v_exp_f32_e32 v7, v7
	v_mul_f32_e32 v14, 0xbcb8aa3b, v82
	v_mul_f32_e32 v8, 0xbcb8aa3b, v76
	v_exp_f32_e32 v9, v9
	v_mul_f32_e32 v16, 0xbcb8aa3b, v83
	v_mul_f32_e32 v11, 0xbcb8aa3b, v77
	v_exp_f32_e32 v14, v14
	v_exp_f32_e32 v8, v8
	v_mul_f32_e32 v15, 0xbcb8aa3b, v78
	v_exp_f32_e32 v16, v16
	v_add_f32_e32 v7, 1.0, v7
	v_exp_f32_e32 v11, v11
	v_mul_f32_e32 v17, 0xbcb8aa3b, v79
	v_rcp_f32_e32 v7, v7
	v_add_f32_e32 v9, 1.0, v9
	v_exp_f32_e32 v15, v15
	v_rcp_f32_e32 v9, v9
	v_add_f32_e32 v14, 1.0, v14
	v_exp_f32_e32 v17, v17
	v_add_f32_e32 v8, 1.0, v8
	v_rcp_f32_e32 v14, v14
	v_add_f32_e32 v16, 1.0, v16
	v_rcp_f32_e32 v8, v8
	v_add_f32_e32 v11, 1.0, v11
	v_rcp_f32_e32 v16, v16
	v_fma_f32 v7, v7, s9, 0.5
	v_rcp_f32_e32 v11, v11
	v_add_f32_e32 v15, 1.0, v15
	v_max_f32_e32 v7, 1.0, v7
	v_fma_f32 v9, v9, s9, 0.5
	v_rcp_f32_e32 v15, v15
	v_add_f32_e32 v17, 1.0, v17
	v_max_f32_e32 v9, 1.0, v9
	v_fma_f32 v14, v14, s9, 0.5
	v_rcp_f32_e32 v17, v17
	v_cvt_pk_u8_f32 v7, v7, 0, 0
	v_fma_f32 v8, v8, s9, 0.5
	v_max_f32_e32 v14, 1.0, v14
	v_fma_f32 v16, v16, s9, 0.5
	v_cvt_pk_u8_f32 v7, v9, 1, v7
	v_max_f32_e32 v8, 1.0, v8
	v_fma_f32 v11, v11, s9, 0.5
	v_max_f32_e32 v16, 1.0, v16
	v_cvt_pk_u8_f32 v7, v14, 2, v7
	v_max_f32_e32 v11, 1.0, v11
	v_fma_f32 v15, v15, s9, 0.5
	v_cvt_pk_u8_f32 v14, v16, 3, v7
	v_cvt_pk_u8_f32 v7, v8, 0, 0
	v_max_f32_e32 v15, 1.0, v15
	v_fma_f32 v17, v17, s9, 0.5
	v_cvt_pk_u8_f32 v7, v11, 1, v7
	v_max_f32_e32 v17, 1.0, v17
	v_cvt_pk_u8_f32 v7, v15, 2, v7
	v_cvt_pk_u8_f32 v15, v17, 3, v7
	v_mul_f32_e32 v7, 0xbcb8aa3b, v88
	v_permlane16_swap_b32_e32 v12, v14
	s_nop 0
	v_permlane16_swap_b32_e32 v13, v15
	v_mul_f32_e32 v9, 0xbcb8aa3b, v89
	v_exp_f32_e32 v7, v7
	global_store_dwordx4 v[4:5], v[12:15], off
	s_nop 0
	v_mul_f32_e32 v8, 0xbcb8aa3b, v84
	v_mul_f32_e32 v12, 0xbcb8aa3b, v90
	v_exp_f32_e32 v9, v9
	v_mul_f32_e32 v14, 0xbcb8aa3b, v91
	v_mul_f32_e32 v11, 0xbcb8aa3b, v85
	v_exp_f32_e32 v12, v12
	v_exp_f32_e32 v8, v8
	v_mul_f32_e32 v13, 0xbcb8aa3b, v86
	v_exp_f32_e32 v14, v14
	v_add_f32_e32 v7, 1.0, v7
	v_exp_f32_e32 v11, v11
	v_mul_f32_e32 v15, 0xbcb8aa3b, v87
	v_rcp_f32_e32 v7, v7
	v_add_f32_e32 v9, 1.0, v9
	v_exp_f32_e32 v13, v13
	v_rcp_f32_e32 v9, v9
	v_add_f32_e32 v12, 1.0, v12
	v_exp_f32_e32 v15, v15
	v_add_f32_e32 v8, 1.0, v8
	v_rcp_f32_e32 v12, v12
	v_add_f32_e32 v14, 1.0, v14
	v_rcp_f32_e32 v8, v8
	v_add_f32_e32 v11, 1.0, v11
	v_rcp_f32_e32 v14, v14
	v_fma_f32 v7, v7, s9, 0.5
	v_rcp_f32_e32 v11, v11
	v_add_f32_e32 v13, 1.0, v13
	v_max_f32_e32 v7, 1.0, v7
	v_fma_f32 v9, v9, s9, 0.5
	v_rcp_f32_e32 v13, v13
	v_add_f32_e32 v15, 1.0, v15
	v_max_f32_e32 v9, 1.0, v9
	v_fma_f32 v12, v12, s9, 0.5
	v_rcp_f32_e32 v15, v15
	v_cvt_pk_u8_f32 v7, v7, 0, 0
	v_fma_f32 v8, v8, s9, 0.5
	v_max_f32_e32 v12, 1.0, v12
	v_fma_f32 v14, v14, s9, 0.5
	v_cvt_pk_u8_f32 v7, v9, 1, v7
	v_max_f32_e32 v8, 1.0, v8
	v_fma_f32 v11, v11, s9, 0.5
	v_max_f32_e32 v14, 1.0, v14
	v_cvt_pk_u8_f32 v7, v12, 2, v7
	v_max_f32_e32 v11, 1.0, v11
	v_fma_f32 v13, v13, s9, 0.5
	v_cvt_pk_u8_f32 v12, v14, 3, v7
	v_cvt_pk_u8_f32 v7, v8, 0, 0
	v_max_f32_e32 v13, 1.0, v13
	v_fma_f32 v15, v15, s9, 0.5
	v_cvt_pk_u8_f32 v7, v11, 1, v7
	v_max_f32_e32 v15, 1.0, v15
	v_cvt_pk_u8_f32 v7, v13, 2, v7
	v_cvt_pk_u8_f32 v13, v15, 3, v7
	v_mul_f32_e32 v7, 0xbcb8aa3b, v72
	v_mul_f32_e32 v9, 0xbcb8aa3b, v73
	v_exp_f32_e32 v7, v7
	v_mul_f32_e32 v14, 0xbcb8aa3b, v74
	v_mul_f32_e32 v8, 0xbcb8aa3b, v68
	v_exp_f32_e32 v9, v9
	v_mul_f32_e32 v16, 0xbcb8aa3b, v75
	v_mul_f32_e32 v11, 0xbcb8aa3b, v69
	v_exp_f32_e32 v14, v14
	v_exp_f32_e32 v8, v8
	v_mul_f32_e32 v15, 0xbcb8aa3b, v70
	v_exp_f32_e32 v16, v16
	v_add_f32_e32 v7, 1.0, v7
	v_exp_f32_e32 v11, v11
	v_mul_f32_e32 v17, 0xbcb8aa3b, v71
	v_rcp_f32_e32 v7, v7
	v_add_f32_e32 v9, 1.0, v9
	v_exp_f32_e32 v15, v15
	v_rcp_f32_e32 v9, v9
	v_add_f32_e32 v14, 1.0, v14
	v_exp_f32_e32 v17, v17
	v_add_f32_e32 v8, 1.0, v8
	v_rcp_f32_e32 v14, v14
	v_add_f32_e32 v16, 1.0, v16
	v_rcp_f32_e32 v8, v8
	v_add_f32_e32 v11, 1.0, v11
	v_rcp_f32_e32 v16, v16
	v_fma_f32 v7, v7, s9, 0.5
	v_rcp_f32_e32 v11, v11
	v_add_f32_e32 v15, 1.0, v15
	v_max_f32_e32 v7, 1.0, v7
	v_fma_f32 v9, v9, s9, 0.5
	v_rcp_f32_e32 v15, v15
	v_add_f32_e32 v17, 1.0, v17
	v_max_f32_e32 v9, 1.0, v9
	v_fma_f32 v14, v14, s9, 0.5
	v_rcp_f32_e32 v17, v17
	v_cvt_pk_u8_f32 v7, v7, 0, 0
	v_fma_f32 v8, v8, s9, 0.5
	v_max_f32_e32 v14, 1.0, v14
	v_fma_f32 v16, v16, s9, 0.5
	v_cvt_pk_u8_f32 v7, v9, 1, v7
	v_max_f32_e32 v8, 1.0, v8
	v_fma_f32 v11, v11, s9, 0.5
	v_max_f32_e32 v16, 1.0, v16
	v_cvt_pk_u8_f32 v7, v14, 2, v7
	v_max_f32_e32 v11, 1.0, v11
	v_fma_f32 v15, v15, s9, 0.5
	v_cvt_pk_u8_f32 v14, v16, 3, v7
	v_cvt_pk_u8_f32 v7, v8, 0, 0
	v_max_f32_e32 v15, 1.0, v15
	v_fma_f32 v17, v17, s9, 0.5
	v_cvt_pk_u8_f32 v7, v11, 1, v7
	v_max_f32_e32 v17, 1.0, v17
	v_cvt_pk_u8_f32 v7, v15, 2, v7
	v_cvt_pk_u8_f32 v15, v17, 3, v7
	v_permlane16_swap_b32_e32 v12, v14
	s_nop 0
	v_permlane16_swap_b32_e32 v13, v15
	global_store_dwordx4 v[4:5], v[12:15], off offset:128
	v_mul_f32_e32 v4, 0xbcb8aa3b, v64
	v_mul_f32_e32 v5, 0xbcb8aa3b, v60
	v_add_u32_e32 v6, 0xa0, v6
	v_mad_i64_i32 v[2:3], s[6:7], v6, s8, v[2:3]
	v_mul_f32_e32 v6, 0xbcb8aa3b, v65
	v_mul_f32_e32 v7, 0xbcb8aa3b, v61
	v_exp_f32_e32 v4, v4
	v_exp_f32_e32 v5, v5
	v_mul_f32_e32 v8, 0xbcb8aa3b, v66
	v_mul_f32_e32 v9, 0xbcb8aa3b, v62
	v_exp_f32_e32 v6, v6
	v_exp_f32_e32 v7, v7
	v_mul_f32_e32 v11, 0xbcb8aa3b, v67
	v_mul_f32_e32 v12, 0xbcb8aa3b, v63
	v_exp_f32_e32 v8, v8
	v_exp_f32_e32 v9, v9
	v_exp_f32_e32 v11, v11
	v_exp_f32_e32 v12, v12
	v_add_f32_e32 v4, 1.0, v4
	v_add_f32_e32 v5, 1.0, v5
	v_rcp_f32_e32 v4, v4
	v_rcp_f32_e32 v5, v5
	v_add_f32_e32 v6, 1.0, v6
	v_add_f32_e32 v7, 1.0, v7
	v_rcp_f32_e32 v6, v6
	v_rcp_f32_e32 v7, v7
	v_add_f32_e32 v8, 1.0, v8
	v_add_f32_e32 v9, 1.0, v9
	v_rcp_f32_e32 v8, v8
	v_rcp_f32_e32 v9, v9
	v_add_f32_e32 v11, 1.0, v11
	v_add_f32_e32 v12, 1.0, v12
	v_rcp_f32_e32 v11, v11
	v_rcp_f32_e32 v12, v12
	v_fma_f32 v4, v4, s9, 0.5
	v_fma_f32 v5, v5, s9, 0.5
	v_max_f32_e32 v4, 1.0, v4
	v_max_f32_e32 v5, 1.0, v5
	v_fma_f32 v6, v6, s9, 0.5
	v_fma_f32 v7, v7, s9, 0.5
	v_max_f32_e32 v6, 1.0, v6
	v_max_f32_e32 v7, 1.0, v7
	v_fma_f32 v8, v8, s9, 0.5
	v_fma_f32 v9, v9, s9, 0.5
	v_cvt_pk_u8_f32 v4, v4, 0, 0
	v_cvt_pk_u8_f32 v5, v5, 0, 0
	v_max_f32_e32 v8, 1.0, v8
	v_max_f32_e32 v9, 1.0, v9
	v_fma_f32 v11, v11, s9, 0.5
	v_fma_f32 v12, v12, s9, 0.5
	v_cvt_pk_u8_f32 v4, v6, 1, v4
	v_cvt_pk_u8_f32 v5, v7, 1, v5
	v_max_f32_e32 v11, 1.0, v11
	v_max_f32_e32 v12, 1.0, v12
	v_cvt_pk_u8_f32 v4, v8, 2, v4
	v_cvt_pk_u8_f32 v5, v9, 2, v5
	v_cvt_pk_u8_f32 v4, v11, 3, v4
	v_cvt_pk_u8_f32 v5, v12, 3, v5
	v_mul_f32_e32 v6, 0xbcb8aa3b, v48
	v_mul_f32_e32 v7, 0xbcb8aa3b, v44
	v_mul_f32_e32 v8, 0xbcb8aa3b, v49
	v_mul_f32_e32 v9, 0xbcb8aa3b, v45
	v_exp_f32_e32 v6, v6
	v_exp_f32_e32 v7, v7
	v_mul_f32_e32 v11, 0xbcb8aa3b, v50
	v_mul_f32_e32 v12, 0xbcb8aa3b, v46
	v_exp_f32_e32 v8, v8
	v_exp_f32_e32 v9, v9
	v_mul_f32_e32 v13, 0xbcb8aa3b, v51
	v_mul_f32_e32 v14, 0xbcb8aa3b, v47
	v_exp_f32_e32 v11, v11
	v_exp_f32_e32 v12, v12
	v_exp_f32_e32 v13, v13
	v_exp_f32_e32 v14, v14
	v_add_f32_e32 v6, 1.0, v6
	v_add_f32_e32 v7, 1.0, v7
	v_rcp_f32_e32 v6, v6
	v_rcp_f32_e32 v7, v7
	v_add_f32_e32 v8, 1.0, v8
	v_add_f32_e32 v9, 1.0, v9
	v_rcp_f32_e32 v8, v8
	v_rcp_f32_e32 v9, v9
	v_add_f32_e32 v11, 1.0, v11
	v_add_f32_e32 v12, 1.0, v12
	v_rcp_f32_e32 v11, v11
	v_rcp_f32_e32 v12, v12
	v_add_f32_e32 v13, 1.0, v13
	v_add_f32_e32 v14, 1.0, v14
	v_rcp_f32_e32 v13, v13
	v_rcp_f32_e32 v14, v14
	v_fma_f32 v6, v6, s9, 0.5
	v_fma_f32 v7, v7, s9, 0.5
	v_max_f32_e32 v6, 1.0, v6
	v_max_f32_e32 v7, 1.0, v7
	v_fma_f32 v8, v8, s9, 0.5
	v_fma_f32 v9, v9, s9, 0.5
	v_max_f32_e32 v8, 1.0, v8
	v_max_f32_e32 v9, 1.0, v9
	v_fma_f32 v11, v11, s9, 0.5
	v_fma_f32 v12, v12, s9, 0.5
	v_cvt_pk_u8_f32 v6, v6, 0, 0
	v_cvt_pk_u8_f32 v7, v7, 0, 0
	v_max_f32_e32 v11, 1.0, v11
	v_max_f32_e32 v12, 1.0, v12
	v_fma_f32 v13, v13, s9, 0.5
	v_fma_f32 v14, v14, s9, 0.5
	v_cvt_pk_u8_f32 v6, v8, 1, v6
	v_cvt_pk_u8_f32 v7, v9, 1, v7
	v_max_f32_e32 v13, 1.0, v13
	v_max_f32_e32 v14, 1.0, v14
	v_cvt_pk_u8_f32 v6, v11, 2, v6
	v_cvt_pk_u8_f32 v7, v12, 2, v7
	v_cvt_pk_u8_f32 v6, v13, 3, v6
	v_cvt_pk_u8_f32 v7, v14, 3, v7
	v_mul_f32_e32 v8, 0xbcb8aa3b, v56
	v_mul_f32_e32 v9, 0xbcb8aa3b, v52
	s_nop 0
	s_nop 0
	v_exp_f32_e32 v8, v8
	v_exp_f32_e32 v9, v9
	v_permlane16_swap_b32_e32 v4, v6
	v_add_f32_e32 v8, 1.0, v8
	v_add_f32_e32 v9, 1.0, v9
	v_rcp_f32_e32 v8, v8
	v_rcp_f32_e32 v9, v9
	v_permlane16_swap_b32_e32 v5, v7
	global_store_dwordx4 v[2:3], v[4:7], off
	v_mul_f32_e32 v11, 0x3c800000, v59
	v_mul_f32_e32 v12, 0x3c800000, v55
	v_mul_f32_e32 v6, 0xbcb8aa3b, v57
	v_mul_f32_e32 v7, 0xbcb8aa3b, v53
	v_fma_f32 v4, v8, s9, 0.5
	v_fma_f32 v5, v9, s9, 0.5
	v_mul_f32_e32 v8, 0xbcb8aa3b, v58
	v_mul_f32_e32 v9, 0xbcb8aa3b, v54
	v_exp_f32_e32 v6, v6
	v_exp_f32_e32 v7, v7
	v_exp_f32_e32 v8, v8
	v_exp_f32_e32 v9, v9
	v_mul_f32_e32 v11, 0xbfb8aa3b, v11
	v_mul_f32_e32 v12, 0xbfb8aa3b, v12
	v_exp_f32_e32 v11, v11
	v_exp_f32_e32 v12, v12
	v_add_f32_e32 v6, 1.0, v6
	v_add_f32_e32 v7, 1.0, v7
	v_rcp_f32_e32 v6, v6
	v_rcp_f32_e32 v7, v7
	v_add_f32_e32 v8, 1.0, v8
	v_add_f32_e32 v9, 1.0, v9
	v_rcp_f32_e32 v8, v8
	v_rcp_f32_e32 v9, v9
	v_add_f32_e32 v11, 1.0, v11
	v_add_f32_e32 v12, 1.0, v12
	v_rcp_f32_e32 v11, v11
	v_rcp_f32_e32 v12, v12
	v_max_f32_e32 v4, 1.0, v4
	v_max_f32_e32 v5, 1.0, v5
	v_fma_f32 v6, v6, s9, 0.5
	v_fma_f32 v7, v7, s9, 0.5
	v_max_f32_e32 v6, 1.0, v6
	v_max_f32_e32 v7, 1.0, v7
	v_fma_f32 v8, v8, s9, 0.5
	v_fma_f32 v9, v9, s9, 0.5
	v_cvt_pk_u8_f32 v4, v4, 0, 0
	v_cvt_pk_u8_f32 v5, v5, 0, 0
	v_max_f32_e32 v8, 1.0, v8
	v_max_f32_e32 v9, 1.0, v9
	v_fma_f32 v11, v11, s9, 0.5
	v_fma_f32 v12, v12, s9, 0.5
	v_cvt_pk_u8_f32 v4, v6, 1, v4
	v_cvt_pk_u8_f32 v5, v7, 1, v5
	v_max_f32_e32 v11, 1.0, v11
	v_max_f32_e32 v12, 1.0, v12
	v_cvt_pk_u8_f32 v4, v8, 2, v4
	v_cvt_pk_u8_f32 v5, v9, 2, v5
	v_cvt_pk_u8_f32 v4, v11, 3, v4
	v_cvt_pk_u8_f32 v5, v12, 3, v5
	v_mul_f32_e32 v6, 0xbcb8aa3b, v40
	v_mul_f32_e32 v7, 0xbcb8aa3b, v36
	v_mul_f32_e32 v8, 0xbcb8aa3b, v41
	v_mul_f32_e32 v9, 0xbcb8aa3b, v37
	v_exp_f32_e32 v6, v6
	v_exp_f32_e32 v7, v7
	v_mul_f32_e32 v11, 0xbcb8aa3b, v42
	v_mul_f32_e32 v12, 0xbcb8aa3b, v38
	v_exp_f32_e32 v8, v8
	v_exp_f32_e32 v9, v9
	v_mul_f32_e32 v13, 0xbcb8aa3b, v43
	v_mul_f32_e32 v14, 0xbcb8aa3b, v39
	v_exp_f32_e32 v11, v11
	v_exp_f32_e32 v12, v12
	v_exp_f32_e32 v13, v13
	v_exp_f32_e32 v14, v14
	v_add_f32_e32 v6, 1.0, v6
	v_add_f32_e32 v7, 1.0, v7
	v_rcp_f32_e32 v6, v6
	v_rcp_f32_e32 v7, v7
	v_add_f32_e32 v8, 1.0, v8
	v_add_f32_e32 v9, 1.0, v9
	v_rcp_f32_e32 v8, v8
	v_rcp_f32_e32 v9, v9
	v_add_f32_e32 v11, 1.0, v11
	v_add_f32_e32 v12, 1.0, v12
	v_rcp_f32_e32 v11, v11
	v_rcp_f32_e32 v12, v12
	v_add_f32_e32 v13, 1.0, v13
	v_add_f32_e32 v14, 1.0, v14
	v_rcp_f32_e32 v13, v13
	v_rcp_f32_e32 v14, v14
	v_fma_f32 v6, v6, s9, 0.5
	v_fma_f32 v7, v7, s9, 0.5
	v_max_f32_e32 v6, 1.0, v6
	v_max_f32_e32 v7, 1.0, v7
	v_fma_f32 v8, v8, s9, 0.5
	v_fma_f32 v9, v9, s9, 0.5
	v_max_f32_e32 v8, 1.0, v8
	v_max_f32_e32 v9, 1.0, v9
	v_fma_f32 v11, v11, s9, 0.5
	v_fma_f32 v12, v12, s9, 0.5
	v_cvt_pk_u8_f32 v6, v6, 0, 0
	v_cvt_pk_u8_f32 v7, v7, 0, 0
	v_max_f32_e32 v11, 1.0, v11
	v_max_f32_e32 v12, 1.0, v12
	v_fma_f32 v13, v13, s9, 0.5
	v_fma_f32 v14, v14, s9, 0.5
	v_cvt_pk_u8_f32 v6, v8, 1, v6
	v_cvt_pk_u8_f32 v7, v9, 1, v7
	v_max_f32_e32 v13, 1.0, v13
	v_max_f32_e32 v14, 1.0, v14
	v_cvt_pk_u8_f32 v6, v11, 2, v6
	v_cvt_pk_u8_f32 v7, v12, 2, v7
	v_cvt_pk_u8_f32 v6, v13, 3, v6
	v_cvt_pk_u8_f32 v7, v14, 3, v7
	s_nop 0
	v_permlane16_swap_b32_e32 v4, v6
	v_permlane16_swap_b32_e32 v5, v7
	global_store_dwordx4 v[2:3], v[4:7], off offset:128
